# v19 plus: compaction pass keeps its running output position in a VGPR (v_bcnt/v_mbcnt) instead of s_bcnt1+s_add+v_add per element
# speedup vs baseline: 1.0010x; 1.0010x over previous
.LBB0_1560:
	s_and_b64 vcc, exec, s[4:5]
	s_cbranch_vccz .LBB0_1831
	v_mov_b32_e32 v206, 0
	v_mov_b32_e32 v135, v30
	v_cmp_ne_u32_e32 vcc, 0, v134
	s_and_saveexec_b64 s[8:9], s[6:7]
	s_cbranch_execz .LBB0_1563
	v_mbcnt_lo_u32_b32 v134, vcc_lo, v206
	v_mbcnt_hi_u32_b32 v134, vcc_hi, v134
	v_lshl_add_u32 v136, v134, 2, s76
	v_lshl_add_u32 v134, v134, 1, s0
	ds_write_b32 v136, v19
	ds_write_b16 v134, v135
.LBB0_1563:
	s_or_b64 exec, exec, s[8:9]
	v_bcnt_u32_b32 v206, vcc_lo, v206
	v_bcnt_u32_b32 v206, vcc_hi, v206
	v_cmp_ge_u32_e32 vcc, v13, v3
	s_and_saveexec_b64 s[6:7], vcc
	s_cbranch_execz .LBB0_1565
	v_mbcnt_lo_u32_b32 v134, vcc_lo, v206
	v_mbcnt_hi_u32_b32 v134, vcc_hi, v134
	v_lshl_add_u32 v136, v134, 2, s76
	ds_write_b32 v136, v13
	v_add_u16_e32 v136, 64, v135
	v_lshl_add_u32 v134, v134, 1, s0
	ds_write_b16 v134, v136
.LBB0_1565:
	s_or_b64 exec, exec, s[6:7]
	v_bcnt_u32_b32 v206, vcc_lo, v206
	v_bcnt_u32_b32 v206, vcc_hi, v206
	v_cmp_ge_u32_e32 vcc, v20, v3
	s_and_saveexec_b64 s[6:7], vcc
	s_cbranch_execz .LBB0_1567
	v_mbcnt_lo_u32_b32 v134, vcc_lo, v206
	v_mbcnt_hi_u32_b32 v134, vcc_hi, v134
	v_lshl_add_u32 v136, v134, 2, s76
	ds_write_b32 v136, v20
	v_add_u16_e32 v136, 0x80, v135
	v_lshl_add_u32 v134, v134, 1, s0
	ds_write_b16 v134, v136
.LBB0_1567:
	s_or_b64 exec, exec, s[6:7]
	v_bcnt_u32_b32 v206, vcc_lo, v206
	v_bcnt_u32_b32 v206, vcc_hi, v206
	v_cmp_ge_u32_e32 vcc, v12, v3
	s_and_saveexec_b64 s[6:7], vcc
	s_cbranch_execz .LBB0_1569
	v_mbcnt_lo_u32_b32 v134, vcc_lo, v206
	v_mbcnt_hi_u32_b32 v134, vcc_hi, v134
	v_lshl_add_u32 v136, v134, 2, s76
	ds_write_b32 v136, v12
	v_add_u16_e32 v136, 0xc0, v135
	v_lshl_add_u32 v134, v134, 1, s0
	ds_write_b16 v134, v136
.LBB0_1569:
	s_or_b64 exec, exec, s[6:7]
	v_bcnt_u32_b32 v206, vcc_lo, v206
	v_bcnt_u32_b32 v206, vcc_hi, v206
	v_cmp_ge_u32_e32 vcc, v18, v3
	s_and_saveexec_b64 s[6:7], vcc
	s_cbranch_execz .LBB0_1571
	v_mbcnt_lo_u32_b32 v134, vcc_lo, v206
	v_mbcnt_hi_u32_b32 v134, vcc_hi, v134
	v_lshl_add_u32 v136, v134, 2, s76
	ds_write_b32 v136, v18
	v_add_u16_e32 v136, 0x100, v135
	v_lshl_add_u32 v134, v134, 1, s0
	ds_write_b16 v134, v136
.LBB0_1571:
	s_or_b64 exec, exec, s[6:7]
	v_bcnt_u32_b32 v206, vcc_lo, v206
	v_bcnt_u32_b32 v206, vcc_hi, v206
	v_cmp_ge_u32_e32 vcc, v10, v3
	s_and_saveexec_b64 s[6:7], vcc
	s_cbranch_execz .LBB0_1573
	v_mbcnt_lo_u32_b32 v134, vcc_lo, v206
	v_mbcnt_hi_u32_b32 v134, vcc_hi, v134
	v_lshl_add_u32 v136, v134, 2, s76
	ds_write_b32 v136, v10
	v_add_u16_e32 v136, 0x140, v135
	v_lshl_add_u32 v134, v134, 1, s0
	ds_write_b16 v134, v136
.LBB0_1573:
	s_or_b64 exec, exec, s[6:7]
	v_bcnt_u32_b32 v206, vcc_lo, v206
	v_bcnt_u32_b32 v206, vcc_hi, v206
	v_cmp_ge_u32_e32 vcc, v17, v3
	s_and_saveexec_b64 s[6:7], vcc
	s_cbranch_execz .LBB0_1575
	v_mbcnt_lo_u32_b32 v134, vcc_lo, v206
	v_mbcnt_hi_u32_b32 v134, vcc_hi, v134
	v_lshl_add_u32 v136, v134, 2, s76
	ds_write_b32 v136, v17
	v_add_u16_e32 v136, 0x180, v135
	v_lshl_add_u32 v134, v134, 1, s0
	ds_write_b16 v134, v136
.LBB0_1575:
	s_or_b64 exec, exec, s[6:7]
	v_bcnt_u32_b32 v206, vcc_lo, v206
	v_bcnt_u32_b32 v206, vcc_hi, v206
	v_cmp_ge_u32_e32 vcc, v9, v3
	s_and_saveexec_b64 s[6:7], vcc
	s_cbranch_execz .LBB0_1577
	v_mbcnt_lo_u32_b32 v134, vcc_lo, v206
	v_mbcnt_hi_u32_b32 v134, vcc_hi, v134
	v_lshl_add_u32 v136, v134, 2, s76
	ds_write_b32 v136, v9
	v_add_u16_e32 v136, 0x1c0, v135
	v_lshl_add_u32 v134, v134, 1, s0
	ds_write_b16 v134, v136
.LBB0_1577:
	s_or_b64 exec, exec, s[6:7]
	v_bcnt_u32_b32 v206, vcc_lo, v206
	v_bcnt_u32_b32 v206, vcc_hi, v206
	v_cmp_ge_u32_e32 vcc, v16, v3
	s_and_saveexec_b64 s[6:7], vcc
	s_cbranch_execz .LBB0_1579
	v_mbcnt_lo_u32_b32 v134, vcc_lo, v206
	v_mbcnt_hi_u32_b32 v134, vcc_hi, v134
	v_lshl_add_u32 v136, v134, 2, s76
	ds_write_b32 v136, v16
	v_add_u16_e32 v136, 0x200, v135
	v_lshl_add_u32 v134, v134, 1, s0
	ds_write_b16 v134, v136
.LBB0_1579:
	s_or_b64 exec, exec, s[6:7]
	v_bcnt_u32_b32 v206, vcc_lo, v206
	v_bcnt_u32_b32 v206, vcc_hi, v206
	v_cmp_ge_u32_e32 vcc, v8, v3
	s_and_saveexec_b64 s[6:7], vcc
	s_cbranch_execz .LBB0_1581
	v_mbcnt_lo_u32_b32 v134, vcc_lo, v206
	v_mbcnt_hi_u32_b32 v134, vcc_hi, v134
	v_lshl_add_u32 v136, v134, 2, s76
	ds_write_b32 v136, v8
	v_add_u16_e32 v136, 0x240, v135
	v_lshl_add_u32 v134, v134, 1, s0
	ds_write_b16 v134, v136
.LBB0_1581:
	s_or_b64 exec, exec, s[6:7]
	v_bcnt_u32_b32 v206, vcc_lo, v206
	v_bcnt_u32_b32 v206, vcc_hi, v206
	v_cmp_ge_u32_e32 vcc, v15, v3
	s_and_saveexec_b64 s[6:7], vcc
	s_cbranch_execz .LBB0_1583
	v_mbcnt_lo_u32_b32 v134, vcc_lo, v206
	v_mbcnt_hi_u32_b32 v134, vcc_hi, v134
	v_lshl_add_u32 v136, v134, 2, s76
	ds_write_b32 v136, v15
	v_add_u16_e32 v136, 0x280, v135
	v_lshl_add_u32 v134, v134, 1, s0
	ds_write_b16 v134, v136
.LBB0_1583:
	s_or_b64 exec, exec, s[6:7]
	v_bcnt_u32_b32 v206, vcc_lo, v206
	v_bcnt_u32_b32 v206, vcc_hi, v206
	v_cmp_ge_u32_e32 vcc, v7, v3
	s_and_saveexec_b64 s[6:7], vcc
	s_cbranch_execz .LBB0_1585
	v_mbcnt_lo_u32_b32 v134, vcc_lo, v206
	v_mbcnt_hi_u32_b32 v134, vcc_hi, v134
	v_lshl_add_u32 v136, v134, 2, s76
	ds_write_b32 v136, v7
	v_add_u16_e32 v136, 0x2c0, v135
	v_lshl_add_u32 v134, v134, 1, s0
	ds_write_b16 v134, v136
.LBB0_1585:
	s_or_b64 exec, exec, s[6:7]
	v_bcnt_u32_b32 v206, vcc_lo, v206
	v_bcnt_u32_b32 v206, vcc_hi, v206
	v_cmp_ge_u32_e32 vcc, v14, v3
	s_and_saveexec_b64 s[6:7], vcc
	s_cbranch_execz .LBB0_1587
	v_mbcnt_lo_u32_b32 v134, vcc_lo, v206
	v_mbcnt_hi_u32_b32 v134, vcc_hi, v134
	v_lshl_add_u32 v136, v134, 2, s76
	ds_write_b32 v136, v14
	v_add_u16_e32 v136, 0x300, v135
	v_lshl_add_u32 v134, v134, 1, s0
	ds_write_b16 v134, v136
.LBB0_1587:
	s_or_b64 exec, exec, s[6:7]
	v_bcnt_u32_b32 v206, vcc_lo, v206
	v_bcnt_u32_b32 v206, vcc_hi, v206
	v_cmp_ge_u32_e32 vcc, v5, v3
	s_and_saveexec_b64 s[6:7], vcc
	s_cbranch_execz .LBB0_1589
	v_mbcnt_lo_u32_b32 v134, vcc_lo, v206
	v_mbcnt_hi_u32_b32 v134, vcc_hi, v134
	v_lshl_add_u32 v136, v134, 2, s76
	ds_write_b32 v136, v5
	v_add_u16_e32 v136, 0x340, v135
	v_lshl_add_u32 v134, v134, 1, s0
	ds_write_b16 v134, v136
.LBB0_1589:
	s_or_b64 exec, exec, s[6:7]
	v_bcnt_u32_b32 v206, vcc_lo, v206
	v_bcnt_u32_b32 v206, vcc_hi, v206
	v_cmp_ge_u32_e32 vcc, v11, v3
	s_and_saveexec_b64 s[6:7], vcc
	s_cbranch_execz .LBB0_1591
	v_mbcnt_lo_u32_b32 v134, vcc_lo, v206
	v_mbcnt_hi_u32_b32 v134, vcc_hi, v134
	v_lshl_add_u32 v136, v134, 2, s76
	ds_write_b32 v136, v11
	v_add_u16_e32 v136, 0x380, v135
	v_lshl_add_u32 v134, v134, 1, s0
	ds_write_b16 v134, v136
.LBB0_1591:
	s_or_b64 exec, exec, s[6:7]
	v_bcnt_u32_b32 v206, vcc_lo, v206
	v_bcnt_u32_b32 v206, vcc_hi, v206
	v_cmp_ge_u32_e32 vcc, v4, v3
	s_and_saveexec_b64 s[6:7], vcc
	s_cbranch_execz .LBB0_1593
	v_mbcnt_lo_u32_b32 v134, vcc_lo, v206
	v_mbcnt_hi_u32_b32 v134, vcc_hi, v134
	v_lshl_add_u32 v136, v134, 2, s76
	v_add_u16_e32 v135, 0x3c0, v135
	v_lshl_add_u32 v134, v134, 1, s0
	ds_write_b32 v136, v4
	ds_write_b16 v134, v135
.LBB0_1593:
	s_or_b64 exec, exec, s[6:7]
	v_bcnt_u32_b32 v206, vcc_lo, v206
	v_bcnt_u32_b32 v206, vcc_hi, v206
	s_andn2_b64 vcc, exec, s[88:89]
	s_cbranch_vccnz .LBB0_1696
	v_mov_b32_e32 v134, v30
	v_cmp_ge_u32_e32 vcc, v22, v3
	s_and_saveexec_b64 s[6:7], vcc
	s_cbranch_execz .LBB0_1596
	v_mbcnt_lo_u32_b32 v135, vcc_lo, v206
	v_mbcnt_hi_u32_b32 v135, vcc_hi, v135
	v_lshl_add_u32 v136, v135, 2, s76
	ds_write_b32 v136, v22
	v_add_u16_e32 v136, 0x400, v134
	v_lshl_add_u32 v135, v135, 1, s0
	ds_write_b16 v135, v136
.LBB0_1596:
	s_or_b64 exec, exec, s[6:7]
	v_bcnt_u32_b32 v206, vcc_lo, v206
	v_bcnt_u32_b32 v206, vcc_hi, v206
	v_cmp_ge_u32_e32 vcc, v21, v3
	s_and_saveexec_b64 s[6:7], vcc
	s_cbranch_execz .LBB0_1598
	v_mbcnt_lo_u32_b32 v135, vcc_lo, v206
	v_mbcnt_hi_u32_b32 v135, vcc_hi, v135
	v_lshl_add_u32 v136, v135, 2, s76
	ds_write_b32 v136, v21
	v_add_u16_e32 v136, 0x440, v134
	v_lshl_add_u32 v135, v135, 1, s0
	ds_write_b16 v135, v136
.LBB0_1598:
	s_or_b64 exec, exec, s[6:7]
	v_bcnt_u32_b32 v206, vcc_lo, v206
	v_bcnt_u32_b32 v206, vcc_hi, v206
	v_cmp_ge_u32_e32 vcc, v24, v3
	s_and_saveexec_b64 s[6:7], vcc
	s_cbranch_execz .LBB0_1600
	v_mbcnt_lo_u32_b32 v135, vcc_lo, v206
	v_mbcnt_hi_u32_b32 v135, vcc_hi, v135
	v_lshl_add_u32 v136, v135, 2, s76
	ds_write_b32 v136, v24
	v_add_u16_e32 v136, 0x480, v134
	v_lshl_add_u32 v135, v135, 1, s0
	ds_write_b16 v135, v136
.LBB0_1600:
	s_or_b64 exec, exec, s[6:7]
	v_bcnt_u32_b32 v206, vcc_lo, v206
	v_bcnt_u32_b32 v206, vcc_hi, v206
	v_cmp_ge_u32_e32 vcc, v23, v3
	s_and_saveexec_b64 s[6:7], vcc
	s_cbranch_execz .LBB0_1602
	v_mbcnt_lo_u32_b32 v135, vcc_lo, v206
	v_mbcnt_hi_u32_b32 v135, vcc_hi, v135
	v_lshl_add_u32 v136, v135, 2, s76
	ds_write_b32 v136, v23
	v_add_u16_e32 v136, 0x4c0, v134
	v_lshl_add_u32 v135, v135, 1, s0
	ds_write_b16 v135, v136
.LBB0_1602:
	s_or_b64 exec, exec, s[6:7]
	v_bcnt_u32_b32 v206, vcc_lo, v206
	v_bcnt_u32_b32 v206, vcc_hi, v206
	v_cmp_ge_u32_e32 vcc, v26, v3
	s_and_saveexec_b64 s[6:7], vcc
	s_cbranch_execz .LBB0_1604
	v_mbcnt_lo_u32_b32 v135, vcc_lo, v206
	v_mbcnt_hi_u32_b32 v135, vcc_hi, v135
	v_lshl_add_u32 v136, v135, 2, s76
	ds_write_b32 v136, v26
	v_add_u16_e32 v136, 0x500, v134
	v_lshl_add_u32 v135, v135, 1, s0
	ds_write_b16 v135, v136
.LBB0_1604:
	s_or_b64 exec, exec, s[6:7]
	v_bcnt_u32_b32 v206, vcc_lo, v206
	v_bcnt_u32_b32 v206, vcc_hi, v206
	v_cmp_ge_u32_e32 vcc, v25, v3
	s_and_saveexec_b64 s[6:7], vcc
	s_cbranch_execz .LBB0_1606
	v_mbcnt_lo_u32_b32 v135, vcc_lo, v206
	v_mbcnt_hi_u32_b32 v135, vcc_hi, v135
	v_lshl_add_u32 v136, v135, 2, s76
	ds_write_b32 v136, v25
	v_add_u16_e32 v136, 0x540, v134
	v_lshl_add_u32 v135, v135, 1, s0
	ds_write_b16 v135, v136
.LBB0_1606:
	s_or_b64 exec, exec, s[6:7]
	v_bcnt_u32_b32 v206, vcc_lo, v206
	v_bcnt_u32_b32 v206, vcc_hi, v206
	v_cmp_ge_u32_e32 vcc, v28, v3
	s_and_saveexec_b64 s[6:7], vcc
	s_cbranch_execz .LBB0_1608
	v_mbcnt_lo_u32_b32 v135, vcc_lo, v206
	v_mbcnt_hi_u32_b32 v135, vcc_hi, v135
	v_lshl_add_u32 v136, v135, 2, s76
	ds_write_b32 v136, v28
	v_add_u16_e32 v136, 0x580, v134
	v_lshl_add_u32 v135, v135, 1, s0
	ds_write_b16 v135, v136
.LBB0_1608:
	s_or_b64 exec, exec, s[6:7]
	v_bcnt_u32_b32 v206, vcc_lo, v206
	v_bcnt_u32_b32 v206, vcc_hi, v206
	v_cmp_ge_u32_e32 vcc, v27, v3
	s_and_saveexec_b64 s[6:7], vcc
	s_cbranch_execz .LBB0_1610
	v_mbcnt_lo_u32_b32 v135, vcc_lo, v206
	v_mbcnt_hi_u32_b32 v135, vcc_hi, v135
	v_lshl_add_u32 v136, v135, 2, s76
	ds_write_b32 v136, v27
	v_add_u16_e32 v136, 0x5c0, v134
	v_lshl_add_u32 v135, v135, 1, s0
	ds_write_b16 v135, v136
.LBB0_1610:
	s_or_b64 exec, exec, s[6:7]
	v_bcnt_u32_b32 v206, vcc_lo, v206
	v_bcnt_u32_b32 v206, vcc_hi, v206
	v_cmp_ge_u32_e32 vcc, v31, v3
	s_and_saveexec_b64 s[6:7], vcc
	s_cbranch_execz .LBB0_1612
	v_mbcnt_lo_u32_b32 v135, vcc_lo, v206
	v_mbcnt_hi_u32_b32 v135, vcc_hi, v135
	v_lshl_add_u32 v136, v135, 2, s76
	ds_write_b32 v136, v31
	v_add_u16_e32 v136, 0x600, v134
	v_lshl_add_u32 v135, v135, 1, s0
	ds_write_b16 v135, v136
.LBB0_1612:
	s_or_b64 exec, exec, s[6:7]
	v_bcnt_u32_b32 v206, vcc_lo, v206
	v_bcnt_u32_b32 v206, vcc_hi, v206
	v_cmp_ge_u32_e32 vcc, v29, v3
	s_and_saveexec_b64 s[6:7], vcc
	s_cbranch_execz .LBB0_1614
	v_mbcnt_lo_u32_b32 v135, vcc_lo, v206
	v_mbcnt_hi_u32_b32 v135, vcc_hi, v135
	v_lshl_add_u32 v136, v135, 2, s76
	ds_write_b32 v136, v29
	v_add_u16_e32 v136, 0x640, v134
	v_lshl_add_u32 v135, v135, 1, s0
	ds_write_b16 v135, v136
.LBB0_1614:
	s_or_b64 exec, exec, s[6:7]
	v_bcnt_u32_b32 v206, vcc_lo, v206
	v_bcnt_u32_b32 v206, vcc_hi, v206
	v_cmp_ge_u32_e32 vcc, v33, v3
	s_and_saveexec_b64 s[6:7], vcc
	s_cbranch_execz .LBB0_1616
	v_mbcnt_lo_u32_b32 v135, vcc_lo, v206
	v_mbcnt_hi_u32_b32 v135, vcc_hi, v135
	v_lshl_add_u32 v136, v135, 2, s76
	ds_write_b32 v136, v33
	v_add_u16_e32 v136, 0x680, v134
	v_lshl_add_u32 v135, v135, 1, s0
	ds_write_b16 v135, v136
.LBB0_1616:
	s_or_b64 exec, exec, s[6:7]
	v_bcnt_u32_b32 v206, vcc_lo, v206
	v_bcnt_u32_b32 v206, vcc_hi, v206
	v_cmp_ge_u32_e32 vcc, v32, v3
	s_and_saveexec_b64 s[6:7], vcc
	s_cbranch_execz .LBB0_1618
	v_mbcnt_lo_u32_b32 v135, vcc_lo, v206
	v_mbcnt_hi_u32_b32 v135, vcc_hi, v135
	v_lshl_add_u32 v136, v135, 2, s76
	ds_write_b32 v136, v32
	v_add_u16_e32 v136, 0x6c0, v134
	v_lshl_add_u32 v135, v135, 1, s0
	ds_write_b16 v135, v136
.LBB0_1618:
	s_or_b64 exec, exec, s[6:7]
	v_bcnt_u32_b32 v206, vcc_lo, v206
	v_bcnt_u32_b32 v206, vcc_hi, v206
	v_cmp_ge_u32_e32 vcc, v35, v3
	s_and_saveexec_b64 s[6:7], vcc
	s_cbranch_execz .LBB0_1620
	v_mbcnt_lo_u32_b32 v135, vcc_lo, v206
	v_mbcnt_hi_u32_b32 v135, vcc_hi, v135
	v_lshl_add_u32 v136, v135, 2, s76
	ds_write_b32 v136, v35
	v_add_u16_e32 v136, 0x700, v134
	v_lshl_add_u32 v135, v135, 1, s0
	ds_write_b16 v135, v136
.LBB0_1620:
	s_or_b64 exec, exec, s[6:7]
	v_bcnt_u32_b32 v206, vcc_lo, v206
	v_bcnt_u32_b32 v206, vcc_hi, v206
	v_cmp_ge_u32_e32 vcc, v34, v3
	s_and_saveexec_b64 s[6:7], vcc
	s_cbranch_execz .LBB0_1622
	v_mbcnt_lo_u32_b32 v135, vcc_lo, v206
	v_mbcnt_hi_u32_b32 v135, vcc_hi, v135
	v_lshl_add_u32 v136, v135, 2, s76
	ds_write_b32 v136, v34
	v_add_u16_e32 v136, 0x740, v134
	v_lshl_add_u32 v135, v135, 1, s0
	ds_write_b16 v135, v136
.LBB0_1622:
	s_or_b64 exec, exec, s[6:7]
	v_bcnt_u32_b32 v206, vcc_lo, v206
	v_bcnt_u32_b32 v206, vcc_hi, v206
	v_cmp_ge_u32_e32 vcc, v37, v3
	s_and_saveexec_b64 s[6:7], vcc
	s_cbranch_execz .LBB0_1624
	v_mbcnt_lo_u32_b32 v135, vcc_lo, v206
	v_mbcnt_hi_u32_b32 v135, vcc_hi, v135
	v_lshl_add_u32 v136, v135, 2, s76
	ds_write_b32 v136, v37
	v_add_u16_e32 v136, 0x780, v134
	v_lshl_add_u32 v135, v135, 1, s0
	ds_write_b16 v135, v136
.LBB0_1624:
	s_or_b64 exec, exec, s[6:7]
	v_bcnt_u32_b32 v206, vcc_lo, v206
	v_bcnt_u32_b32 v206, vcc_hi, v206
	v_cmp_ge_u32_e32 vcc, v36, v3
	s_and_saveexec_b64 s[6:7], vcc
	s_cbranch_execz .LBB0_1626
	v_mbcnt_lo_u32_b32 v135, vcc_lo, v206
	v_mbcnt_hi_u32_b32 v135, vcc_hi, v135
	v_lshl_add_u32 v136, v135, 2, s76
	v_add_u16_e32 v134, 0x7c0, v134
	v_lshl_add_u32 v135, v135, 1, s0
	ds_write_b32 v136, v36
	ds_write_b16 v135, v134
.LBB0_1626:
	s_or_b64 exec, exec, s[6:7]
	v_bcnt_u32_b32 v206, vcc_lo, v206
	v_bcnt_u32_b32 v206, vcc_hi, v206
	s_andn2_b64 vcc, exec, s[66:67]
	s_cbranch_vccz .LBB0_1697

.LBB0_1628:
	v_mov_b32_e32 v134, v30
	v_cmp_ge_u32_e32 vcc, v55, v3
	s_and_saveexec_b64 s[6:7], vcc
	s_cbranch_execz .LBB0_1630
	v_mbcnt_lo_u32_b32 v135, vcc_lo, v206
	v_mbcnt_hi_u32_b32 v135, vcc_hi, v135
	v_lshl_add_u32 v136, v135, 2, s76
	ds_write_b32 v136, v55
	v_add_u16_e32 v136, 0xc00, v134
	v_lshl_add_u32 v135, v135, 1, s0
	ds_write_b16 v135, v136
.LBB0_1630:
	s_or_b64 exec, exec, s[6:7]
	v_bcnt_u32_b32 v206, vcc_lo, v206
	v_bcnt_u32_b32 v206, vcc_hi, v206
	v_cmp_ge_u32_e32 vcc, v54, v3
	s_and_saveexec_b64 s[6:7], vcc
	s_cbranch_execz .LBB0_1632
	v_mbcnt_lo_u32_b32 v135, vcc_lo, v206
	v_mbcnt_hi_u32_b32 v135, vcc_hi, v135
	v_lshl_add_u32 v136, v135, 2, s76
	ds_write_b32 v136, v54
	v_add_u16_e32 v136, 0xc40, v134
	v_lshl_add_u32 v135, v135, 1, s0
	ds_write_b16 v135, v136
.LBB0_1632:
	s_or_b64 exec, exec, s[6:7]
	v_bcnt_u32_b32 v206, vcc_lo, v206
	v_bcnt_u32_b32 v206, vcc_hi, v206
	v_cmp_ge_u32_e32 vcc, v57, v3
	s_and_saveexec_b64 s[6:7], vcc
	s_cbranch_execz .LBB0_1634
	v_mbcnt_lo_u32_b32 v135, vcc_lo, v206
	v_mbcnt_hi_u32_b32 v135, vcc_hi, v135
	v_lshl_add_u32 v136, v135, 2, s76
	ds_write_b32 v136, v57
	v_add_u16_e32 v136, 0xc80, v134
	v_lshl_add_u32 v135, v135, 1, s0
	ds_write_b16 v135, v136
.LBB0_1634:
	s_or_b64 exec, exec, s[6:7]
	v_bcnt_u32_b32 v206, vcc_lo, v206
	v_bcnt_u32_b32 v206, vcc_hi, v206
	v_cmp_ge_u32_e32 vcc, v56, v3
	s_and_saveexec_b64 s[6:7], vcc
	s_cbranch_execz .LBB0_1636
	v_mbcnt_lo_u32_b32 v135, vcc_lo, v206
	v_mbcnt_hi_u32_b32 v135, vcc_hi, v135
	v_lshl_add_u32 v136, v135, 2, s76
	ds_write_b32 v136, v56
	v_add_u16_e32 v136, 0xcc0, v134
	v_lshl_add_u32 v135, v135, 1, s0
	ds_write_b16 v135, v136
.LBB0_1636:
	s_or_b64 exec, exec, s[6:7]
	v_bcnt_u32_b32 v206, vcc_lo, v206
	v_bcnt_u32_b32 v206, vcc_hi, v206
	v_cmp_ge_u32_e32 vcc, v59, v3
	s_and_saveexec_b64 s[6:7], vcc
	s_cbranch_execz .LBB0_1638
	v_mbcnt_lo_u32_b32 v135, vcc_lo, v206
	v_mbcnt_hi_u32_b32 v135, vcc_hi, v135
	v_lshl_add_u32 v136, v135, 2, s76
	ds_write_b32 v136, v59
	v_add_u16_e32 v136, 0xd00, v134
	v_lshl_add_u32 v135, v135, 1, s0
	ds_write_b16 v135, v136
.LBB0_1638:
	s_or_b64 exec, exec, s[6:7]
	v_bcnt_u32_b32 v206, vcc_lo, v206
	v_bcnt_u32_b32 v206, vcc_hi, v206
	v_cmp_ge_u32_e32 vcc, v58, v3
	s_and_saveexec_b64 s[6:7], vcc
	s_cbranch_execz .LBB0_1640
	v_mbcnt_lo_u32_b32 v135, vcc_lo, v206
	v_mbcnt_hi_u32_b32 v135, vcc_hi, v135
	v_lshl_add_u32 v136, v135, 2, s76
	ds_write_b32 v136, v58
	v_add_u16_e32 v136, 0xd40, v134
	v_lshl_add_u32 v135, v135, 1, s0
	ds_write_b16 v135, v136
.LBB0_1640:
	s_or_b64 exec, exec, s[6:7]
	v_bcnt_u32_b32 v206, vcc_lo, v206
	v_bcnt_u32_b32 v206, vcc_hi, v206
	v_cmp_ge_u32_e32 vcc, v61, v3
	s_and_saveexec_b64 s[6:7], vcc
	s_cbranch_execz .LBB0_1642
	v_mbcnt_lo_u32_b32 v135, vcc_lo, v206
	v_mbcnt_hi_u32_b32 v135, vcc_hi, v135
	v_lshl_add_u32 v136, v135, 2, s76
	ds_write_b32 v136, v61
	v_add_u16_e32 v136, 0xd80, v134
	v_lshl_add_u32 v135, v135, 1, s0
	ds_write_b16 v135, v136
.LBB0_1642:
	s_or_b64 exec, exec, s[6:7]
	v_bcnt_u32_b32 v206, vcc_lo, v206
	v_bcnt_u32_b32 v206, vcc_hi, v206
	v_cmp_ge_u32_e32 vcc, v60, v3
	s_and_saveexec_b64 s[6:7], vcc
	s_cbranch_execz .LBB0_1644
	v_mbcnt_lo_u32_b32 v135, vcc_lo, v206
	v_mbcnt_hi_u32_b32 v135, vcc_hi, v135
	v_lshl_add_u32 v136, v135, 2, s76
	ds_write_b32 v136, v60
	v_add_u16_e32 v136, 0xdc0, v134
	v_lshl_add_u32 v135, v135, 1, s0
	ds_write_b16 v135, v136
.LBB0_1644:
	s_or_b64 exec, exec, s[6:7]
	v_bcnt_u32_b32 v206, vcc_lo, v206
	v_bcnt_u32_b32 v206, vcc_hi, v206
	v_cmp_ge_u32_e32 vcc, v63, v3
	s_and_saveexec_b64 s[6:7], vcc
	s_cbranch_execz .LBB0_1646
	v_mbcnt_lo_u32_b32 v135, vcc_lo, v206
	v_mbcnt_hi_u32_b32 v135, vcc_hi, v135
	v_lshl_add_u32 v136, v135, 2, s76
	ds_write_b32 v136, v63
	v_add_u16_e32 v136, 0xe00, v134
	v_lshl_add_u32 v135, v135, 1, s0
	ds_write_b16 v135, v136
.LBB0_1646:
	s_or_b64 exec, exec, s[6:7]
	v_bcnt_u32_b32 v206, vcc_lo, v206
	v_bcnt_u32_b32 v206, vcc_hi, v206
	v_cmp_ge_u32_e32 vcc, v62, v3
	s_and_saveexec_b64 s[6:7], vcc
	s_cbranch_execz .LBB0_1648
	v_mbcnt_lo_u32_b32 v135, vcc_lo, v206
	v_mbcnt_hi_u32_b32 v135, vcc_hi, v135
	v_lshl_add_u32 v136, v135, 2, s76
	ds_write_b32 v136, v62
	v_add_u16_e32 v136, 0xe40, v134
	v_lshl_add_u32 v135, v135, 1, s0
	ds_write_b16 v135, v136
.LBB0_1648:
	s_or_b64 exec, exec, s[6:7]
	v_bcnt_u32_b32 v206, vcc_lo, v206
	v_bcnt_u32_b32 v206, vcc_hi, v206
	v_cmp_ge_u32_e32 vcc, v65, v3
	s_and_saveexec_b64 s[6:7], vcc
	s_cbranch_execz .LBB0_1650
	v_mbcnt_lo_u32_b32 v135, vcc_lo, v206
	v_mbcnt_hi_u32_b32 v135, vcc_hi, v135
	v_lshl_add_u32 v136, v135, 2, s76
	ds_write_b32 v136, v65
	v_add_u16_e32 v136, 0xe80, v134
	v_lshl_add_u32 v135, v135, 1, s0
	ds_write_b16 v135, v136
.LBB0_1650:
	s_or_b64 exec, exec, s[6:7]
	v_bcnt_u32_b32 v206, vcc_lo, v206
	v_bcnt_u32_b32 v206, vcc_hi, v206
	v_cmp_ge_u32_e32 vcc, v64, v3
	s_and_saveexec_b64 s[6:7], vcc
	s_cbranch_execz .LBB0_1652
	v_mbcnt_lo_u32_b32 v135, vcc_lo, v206
	v_mbcnt_hi_u32_b32 v135, vcc_hi, v135
	v_lshl_add_u32 v136, v135, 2, s76
	ds_write_b32 v136, v64
	v_add_u16_e32 v136, 0xec0, v134
	v_lshl_add_u32 v135, v135, 1, s0
	ds_write_b16 v135, v136
.LBB0_1652:
	s_or_b64 exec, exec, s[6:7]
	v_bcnt_u32_b32 v206, vcc_lo, v206
	v_bcnt_u32_b32 v206, vcc_hi, v206
	v_cmp_ge_u32_e32 vcc, v67, v3
	s_and_saveexec_b64 s[6:7], vcc
	s_cbranch_execz .LBB0_1654
	v_mbcnt_lo_u32_b32 v135, vcc_lo, v206
	v_mbcnt_hi_u32_b32 v135, vcc_hi, v135
	v_lshl_add_u32 v136, v135, 2, s76
	ds_write_b32 v136, v67
	v_add_u16_e32 v136, 0xf00, v134
	v_lshl_add_u32 v135, v135, 1, s0
	ds_write_b16 v135, v136
.LBB0_1654:
	s_or_b64 exec, exec, s[6:7]
	v_bcnt_u32_b32 v206, vcc_lo, v206
	v_bcnt_u32_b32 v206, vcc_hi, v206
	v_cmp_ge_u32_e32 vcc, v66, v3
	s_and_saveexec_b64 s[6:7], vcc
	s_cbranch_execz .LBB0_1656
	v_mbcnt_lo_u32_b32 v135, vcc_lo, v206
	v_mbcnt_hi_u32_b32 v135, vcc_hi, v135
	v_lshl_add_u32 v136, v135, 2, s76
	ds_write_b32 v136, v66
	v_add_u16_e32 v136, 0xf40, v134
	v_lshl_add_u32 v135, v135, 1, s0
	ds_write_b16 v135, v136
.LBB0_1656:
	s_or_b64 exec, exec, s[6:7]
	v_bcnt_u32_b32 v206, vcc_lo, v206
	v_bcnt_u32_b32 v206, vcc_hi, v206
	v_cmp_ge_u32_e32 vcc, v69, v3
	s_and_saveexec_b64 s[6:7], vcc
	s_cbranch_execz .LBB0_1658
	v_mbcnt_lo_u32_b32 v135, vcc_lo, v206
	v_mbcnt_hi_u32_b32 v135, vcc_hi, v135
	v_lshl_add_u32 v136, v135, 2, s76
	ds_write_b32 v136, v69
	v_add_u16_e32 v136, 0xf80, v134
	v_lshl_add_u32 v135, v135, 1, s0
	ds_write_b16 v135, v136
.LBB0_1658:
	s_or_b64 exec, exec, s[6:7]
	v_bcnt_u32_b32 v206, vcc_lo, v206
	v_bcnt_u32_b32 v206, vcc_hi, v206
	v_cmp_ge_u32_e32 vcc, v68, v3
	s_and_saveexec_b64 s[6:7], vcc
	s_cbranch_execz .LBB0_1660
	v_mbcnt_lo_u32_b32 v135, vcc_lo, v206
	v_mbcnt_hi_u32_b32 v135, vcc_hi, v135
	v_lshl_add_u32 v136, v135, 2, s76
	v_add_u16_e32 v134, 0xfc0, v134
	v_lshl_add_u32 v135, v135, 1, s0
	ds_write_b32 v136, v68
	ds_write_b16 v135, v134
.LBB0_1660:
	s_or_b64 exec, exec, s[6:7]
	v_bcnt_u32_b32 v206, vcc_lo, v206
	v_bcnt_u32_b32 v206, vcc_hi, v206
	s_andn2_b64 vcc, exec, s[62:63]
	s_cbranch_vccz .LBB0_1731

.LBB0_1662:
	v_mov_b32_e32 v134, v30
	v_cmp_ge_u32_e32 vcc, v87, v3
	s_and_saveexec_b64 s[6:7], vcc
	s_cbranch_execz .LBB0_1664
	v_mbcnt_lo_u32_b32 v135, vcc_lo, v206
	v_mbcnt_hi_u32_b32 v135, vcc_hi, v135
	v_lshl_add_u32 v136, v135, 2, s76
	ds_write_b32 v136, v87
	v_add_u16_e32 v136, 0x1400, v134
	v_lshl_add_u32 v135, v135, 1, s0
	ds_write_b16 v135, v136
.LBB0_1664:
	s_or_b64 exec, exec, s[6:7]
	v_bcnt_u32_b32 v206, vcc_lo, v206
	v_bcnt_u32_b32 v206, vcc_hi, v206
	v_cmp_ge_u32_e32 vcc, v86, v3
	s_and_saveexec_b64 s[6:7], vcc
	s_cbranch_execz .LBB0_1666
	v_mbcnt_lo_u32_b32 v135, vcc_lo, v206
	v_mbcnt_hi_u32_b32 v135, vcc_hi, v135
	v_lshl_add_u32 v136, v135, 2, s76
	ds_write_b32 v136, v86
	v_add_u16_e32 v136, 0x1440, v134
	v_lshl_add_u32 v135, v135, 1, s0
	ds_write_b16 v135, v136
.LBB0_1666:
	s_or_b64 exec, exec, s[6:7]
	v_bcnt_u32_b32 v206, vcc_lo, v206
	v_bcnt_u32_b32 v206, vcc_hi, v206
	v_cmp_ge_u32_e32 vcc, v89, v3
	s_and_saveexec_b64 s[6:7], vcc
	s_cbranch_execz .LBB0_1668
	v_mbcnt_lo_u32_b32 v135, vcc_lo, v206
	v_mbcnt_hi_u32_b32 v135, vcc_hi, v135
	v_lshl_add_u32 v136, v135, 2, s76
	ds_write_b32 v136, v89
	v_add_u16_e32 v136, 0x1480, v134
	v_lshl_add_u32 v135, v135, 1, s0
	ds_write_b16 v135, v136
.LBB0_1668:
	s_or_b64 exec, exec, s[6:7]
	v_bcnt_u32_b32 v206, vcc_lo, v206
	v_bcnt_u32_b32 v206, vcc_hi, v206
	v_cmp_ge_u32_e32 vcc, v88, v3
	s_and_saveexec_b64 s[6:7], vcc
	s_cbranch_execz .LBB0_1670
	v_mbcnt_lo_u32_b32 v135, vcc_lo, v206
	v_mbcnt_hi_u32_b32 v135, vcc_hi, v135
	v_lshl_add_u32 v136, v135, 2, s76
	ds_write_b32 v136, v88
	v_add_u16_e32 v136, 0x14c0, v134
	v_lshl_add_u32 v135, v135, 1, s0
	ds_write_b16 v135, v136
.LBB0_1670:
	s_or_b64 exec, exec, s[6:7]
	v_bcnt_u32_b32 v206, vcc_lo, v206
	v_bcnt_u32_b32 v206, vcc_hi, v206
	v_cmp_ge_u32_e32 vcc, v91, v3
	s_and_saveexec_b64 s[6:7], vcc
	s_cbranch_execz .LBB0_1672
	v_mbcnt_lo_u32_b32 v135, vcc_lo, v206
	v_mbcnt_hi_u32_b32 v135, vcc_hi, v135
	v_lshl_add_u32 v136, v135, 2, s76
	ds_write_b32 v136, v91
	v_add_u16_e32 v136, 0x1500, v134
	v_lshl_add_u32 v135, v135, 1, s0
	ds_write_b16 v135, v136
.LBB0_1672:
	s_or_b64 exec, exec, s[6:7]
	v_bcnt_u32_b32 v206, vcc_lo, v206
	v_bcnt_u32_b32 v206, vcc_hi, v206
	v_cmp_ge_u32_e32 vcc, v90, v3
	s_and_saveexec_b64 s[6:7], vcc
	s_cbranch_execz .LBB0_1674
	v_mbcnt_lo_u32_b32 v135, vcc_lo, v206
	v_mbcnt_hi_u32_b32 v135, vcc_hi, v135
	v_lshl_add_u32 v136, v135, 2, s76
	ds_write_b32 v136, v90
	v_add_u16_e32 v136, 0x1540, v134
	v_lshl_add_u32 v135, v135, 1, s0
	ds_write_b16 v135, v136
.LBB0_1674:
	s_or_b64 exec, exec, s[6:7]
	v_bcnt_u32_b32 v206, vcc_lo, v206
	v_bcnt_u32_b32 v206, vcc_hi, v206
	v_cmp_ge_u32_e32 vcc, v93, v3
	s_and_saveexec_b64 s[6:7], vcc
	s_cbranch_execz .LBB0_1676
	v_mbcnt_lo_u32_b32 v135, vcc_lo, v206
	v_mbcnt_hi_u32_b32 v135, vcc_hi, v135
	v_lshl_add_u32 v136, v135, 2, s76
	ds_write_b32 v136, v93
	v_add_u16_e32 v136, 0x1580, v134
	v_lshl_add_u32 v135, v135, 1, s0
	ds_write_b16 v135, v136
.LBB0_1676:
	s_or_b64 exec, exec, s[6:7]
	v_bcnt_u32_b32 v206, vcc_lo, v206
	v_bcnt_u32_b32 v206, vcc_hi, v206
	v_cmp_ge_u32_e32 vcc, v92, v3
	s_and_saveexec_b64 s[6:7], vcc
	s_cbranch_execz .LBB0_1678
	v_mbcnt_lo_u32_b32 v135, vcc_lo, v206
	v_mbcnt_hi_u32_b32 v135, vcc_hi, v135
	v_lshl_add_u32 v136, v135, 2, s76
	ds_write_b32 v136, v92
	v_add_u16_e32 v136, 0x15c0, v134
	v_lshl_add_u32 v135, v135, 1, s0
	ds_write_b16 v135, v136
.LBB0_1678:
	s_or_b64 exec, exec, s[6:7]
	v_bcnt_u32_b32 v206, vcc_lo, v206
	v_bcnt_u32_b32 v206, vcc_hi, v206
	v_cmp_ge_u32_e32 vcc, v95, v3
	s_and_saveexec_b64 s[6:7], vcc
	s_cbranch_execz .LBB0_1680
	v_mbcnt_lo_u32_b32 v135, vcc_lo, v206
	v_mbcnt_hi_u32_b32 v135, vcc_hi, v135
	v_lshl_add_u32 v136, v135, 2, s76
	ds_write_b32 v136, v95
	v_add_u16_e32 v136, 0x1600, v134
	v_lshl_add_u32 v135, v135, 1, s0
	ds_write_b16 v135, v136
.LBB0_1680:
	s_or_b64 exec, exec, s[6:7]
	v_bcnt_u32_b32 v206, vcc_lo, v206
	v_bcnt_u32_b32 v206, vcc_hi, v206
	v_cmp_ge_u32_e32 vcc, v94, v3
	s_and_saveexec_b64 s[6:7], vcc
	s_cbranch_execz .LBB0_1682
	v_mbcnt_lo_u32_b32 v135, vcc_lo, v206
	v_mbcnt_hi_u32_b32 v135, vcc_hi, v135
	v_lshl_add_u32 v136, v135, 2, s76
	ds_write_b32 v136, v94
	v_add_u16_e32 v136, 0x1640, v134
	v_lshl_add_u32 v135, v135, 1, s0
	ds_write_b16 v135, v136
.LBB0_1682:
	s_or_b64 exec, exec, s[6:7]
	v_bcnt_u32_b32 v206, vcc_lo, v206
	v_bcnt_u32_b32 v206, vcc_hi, v206
	v_cmp_ge_u32_e32 vcc, v97, v3
	s_and_saveexec_b64 s[6:7], vcc
	s_cbranch_execz .LBB0_1684
	v_mbcnt_lo_u32_b32 v135, vcc_lo, v206
	v_mbcnt_hi_u32_b32 v135, vcc_hi, v135
	v_lshl_add_u32 v136, v135, 2, s76
	ds_write_b32 v136, v97
	v_add_u16_e32 v136, 0x1680, v134
	v_lshl_add_u32 v135, v135, 1, s0
	ds_write_b16 v135, v136
.LBB0_1684:
	s_or_b64 exec, exec, s[6:7]
	v_bcnt_u32_b32 v206, vcc_lo, v206
	v_bcnt_u32_b32 v206, vcc_hi, v206
	v_cmp_ge_u32_e32 vcc, v96, v3
	s_and_saveexec_b64 s[6:7], vcc
	s_cbranch_execz .LBB0_1686
	v_mbcnt_lo_u32_b32 v135, vcc_lo, v206
	v_mbcnt_hi_u32_b32 v135, vcc_hi, v135
	v_lshl_add_u32 v136, v135, 2, s76
	ds_write_b32 v136, v96
	v_add_u16_e32 v136, 0x16c0, v134
	v_lshl_add_u32 v135, v135, 1, s0
	ds_write_b16 v135, v136
.LBB0_1686:
	s_or_b64 exec, exec, s[6:7]
	v_bcnt_u32_b32 v206, vcc_lo, v206
	v_bcnt_u32_b32 v206, vcc_hi, v206
	v_cmp_ge_u32_e32 vcc, v99, v3
	s_and_saveexec_b64 s[6:7], vcc
	s_cbranch_execz .LBB0_1688
	v_mbcnt_lo_u32_b32 v135, vcc_lo, v206
	v_mbcnt_hi_u32_b32 v135, vcc_hi, v135
	v_lshl_add_u32 v136, v135, 2, s76
	ds_write_b32 v136, v99
	v_add_u16_e32 v136, 0x1700, v134
	v_lshl_add_u32 v135, v135, 1, s0
	ds_write_b16 v135, v136
.LBB0_1688:
	s_or_b64 exec, exec, s[6:7]
	v_bcnt_u32_b32 v206, vcc_lo, v206
	v_bcnt_u32_b32 v206, vcc_hi, v206
	v_cmp_ge_u32_e32 vcc, v98, v3
	s_and_saveexec_b64 s[6:7], vcc
	s_cbranch_execz .LBB0_1690
	v_mbcnt_lo_u32_b32 v135, vcc_lo, v206
	v_mbcnt_hi_u32_b32 v135, vcc_hi, v135
	v_lshl_add_u32 v136, v135, 2, s76
	ds_write_b32 v136, v98
	v_add_u16_e32 v136, 0x1740, v134
	v_lshl_add_u32 v135, v135, 1, s0
	ds_write_b16 v135, v136
.LBB0_1690:
	s_or_b64 exec, exec, s[6:7]
	v_bcnt_u32_b32 v206, vcc_lo, v206
	v_bcnt_u32_b32 v206, vcc_hi, v206
	v_cmp_ge_u32_e32 vcc, v101, v3
	s_and_saveexec_b64 s[6:7], vcc
	s_cbranch_execz .LBB0_1692
	v_mbcnt_lo_u32_b32 v135, vcc_lo, v206
	v_mbcnt_hi_u32_b32 v135, vcc_hi, v135
	v_lshl_add_u32 v136, v135, 2, s76
	ds_write_b32 v136, v101
	v_add_u16_e32 v136, 0x1780, v134
	v_lshl_add_u32 v135, v135, 1, s0
	ds_write_b16 v135, v136
.LBB0_1692:
	s_or_b64 exec, exec, s[6:7]
	v_bcnt_u32_b32 v206, vcc_lo, v206
	v_bcnt_u32_b32 v206, vcc_hi, v206
	v_cmp_ge_u32_e32 vcc, v100, v3
	s_and_saveexec_b64 s[6:7], vcc
	s_cbranch_execz .LBB0_1694
	v_mbcnt_lo_u32_b32 v135, vcc_lo, v206
	v_mbcnt_hi_u32_b32 v135, vcc_hi, v135
	v_lshl_add_u32 v136, v135, 2, s76
	v_add_u16_e32 v134, 0x17c0, v134
	v_lshl_add_u32 v135, v135, 1, s0
	ds_write_b32 v136, v100
	ds_write_b16 v135, v134
.LBB0_1694:
	s_or_b64 exec, exec, s[6:7]
	v_bcnt_u32_b32 v206, vcc_lo, v206
	v_bcnt_u32_b32 v206, vcc_hi, v206
	s_andn2_b64 vcc, exec, s[58:59]
	s_cbranch_vccz .LBB0_1765

.LBB0_1697:
	v_mov_b32_e32 v134, v30
	v_cmp_ge_u32_e32 vcc, v39, v3
	s_and_saveexec_b64 s[6:7], vcc
	s_cbranch_execz .LBB0_1699
	v_mbcnt_lo_u32_b32 v135, vcc_lo, v206
	v_mbcnt_hi_u32_b32 v135, vcc_hi, v135
	v_lshl_add_u32 v136, v135, 2, s76
	ds_write_b32 v136, v39
	v_add_u16_e32 v136, 0x800, v134
	v_lshl_add_u32 v135, v135, 1, s0
	ds_write_b16 v135, v136
.LBB0_1699:
	s_or_b64 exec, exec, s[6:7]
	v_bcnt_u32_b32 v206, vcc_lo, v206
	v_bcnt_u32_b32 v206, vcc_hi, v206
	v_cmp_ge_u32_e32 vcc, v38, v3
	s_and_saveexec_b64 s[6:7], vcc
	s_cbranch_execz .LBB0_1701
	v_mbcnt_lo_u32_b32 v135, vcc_lo, v206
	v_mbcnt_hi_u32_b32 v135, vcc_hi, v135
	v_lshl_add_u32 v136, v135, 2, s76
	ds_write_b32 v136, v38
	v_add_u16_e32 v136, 0x840, v134
	v_lshl_add_u32 v135, v135, 1, s0
	ds_write_b16 v135, v136
.LBB0_1701:
	s_or_b64 exec, exec, s[6:7]
	v_bcnt_u32_b32 v206, vcc_lo, v206
	v_bcnt_u32_b32 v206, vcc_hi, v206
	v_cmp_ge_u32_e32 vcc, v41, v3
	s_and_saveexec_b64 s[6:7], vcc
	s_cbranch_execz .LBB0_1703
	v_mbcnt_lo_u32_b32 v135, vcc_lo, v206
	v_mbcnt_hi_u32_b32 v135, vcc_hi, v135
	v_lshl_add_u32 v136, v135, 2, s76
	ds_write_b32 v136, v41
	v_add_u16_e32 v136, 0x880, v134
	v_lshl_add_u32 v135, v135, 1, s0
	ds_write_b16 v135, v136
.LBB0_1703:
	s_or_b64 exec, exec, s[6:7]
	v_bcnt_u32_b32 v206, vcc_lo, v206
	v_bcnt_u32_b32 v206, vcc_hi, v206
	v_cmp_ge_u32_e32 vcc, v40, v3
	s_and_saveexec_b64 s[6:7], vcc
	s_cbranch_execz .LBB0_1705
	v_mbcnt_lo_u32_b32 v135, vcc_lo, v206
	v_mbcnt_hi_u32_b32 v135, vcc_hi, v135
	v_lshl_add_u32 v136, v135, 2, s76
	ds_write_b32 v136, v40
	v_add_u16_e32 v136, 0x8c0, v134
	v_lshl_add_u32 v135, v135, 1, s0
	ds_write_b16 v135, v136
.LBB0_1705:
	s_or_b64 exec, exec, s[6:7]
	v_bcnt_u32_b32 v206, vcc_lo, v206
	v_bcnt_u32_b32 v206, vcc_hi, v206
	v_cmp_ge_u32_e32 vcc, v43, v3
	s_and_saveexec_b64 s[6:7], vcc
	s_cbranch_execz .LBB0_1707
	v_mbcnt_lo_u32_b32 v135, vcc_lo, v206
	v_mbcnt_hi_u32_b32 v135, vcc_hi, v135
	v_lshl_add_u32 v136, v135, 2, s76
	ds_write_b32 v136, v43
	v_add_u16_e32 v136, 0x900, v134
	v_lshl_add_u32 v135, v135, 1, s0
	ds_write_b16 v135, v136
.LBB0_1707:
	s_or_b64 exec, exec, s[6:7]
	v_bcnt_u32_b32 v206, vcc_lo, v206
	v_bcnt_u32_b32 v206, vcc_hi, v206
	v_cmp_ge_u32_e32 vcc, v42, v3
	s_and_saveexec_b64 s[6:7], vcc
	s_cbranch_execz .LBB0_1709
	v_mbcnt_lo_u32_b32 v135, vcc_lo, v206
	v_mbcnt_hi_u32_b32 v135, vcc_hi, v135
	v_lshl_add_u32 v136, v135, 2, s76
	ds_write_b32 v136, v42
	v_add_u16_e32 v136, 0x940, v134
	v_lshl_add_u32 v135, v135, 1, s0
	ds_write_b16 v135, v136
.LBB0_1709:
	s_or_b64 exec, exec, s[6:7]
	v_bcnt_u32_b32 v206, vcc_lo, v206
	v_bcnt_u32_b32 v206, vcc_hi, v206
	v_cmp_ge_u32_e32 vcc, v45, v3
	s_and_saveexec_b64 s[6:7], vcc
	s_cbranch_execz .LBB0_1711
	v_mbcnt_lo_u32_b32 v135, vcc_lo, v206
	v_mbcnt_hi_u32_b32 v135, vcc_hi, v135
	v_lshl_add_u32 v136, v135, 2, s76
	ds_write_b32 v136, v45
	v_add_u16_e32 v136, 0x980, v134
	v_lshl_add_u32 v135, v135, 1, s0
	ds_write_b16 v135, v136
.LBB0_1711:
	s_or_b64 exec, exec, s[6:7]
	v_bcnt_u32_b32 v206, vcc_lo, v206
	v_bcnt_u32_b32 v206, vcc_hi, v206
	v_cmp_ge_u32_e32 vcc, v44, v3
	s_and_saveexec_b64 s[6:7], vcc
	s_cbranch_execz .LBB0_1713
	v_mbcnt_lo_u32_b32 v135, vcc_lo, v206
	v_mbcnt_hi_u32_b32 v135, vcc_hi, v135
	v_lshl_add_u32 v136, v135, 2, s76
	ds_write_b32 v136, v44
	v_add_u16_e32 v136, 0x9c0, v134
	v_lshl_add_u32 v135, v135, 1, s0
	ds_write_b16 v135, v136
.LBB0_1713:
	s_or_b64 exec, exec, s[6:7]
	v_bcnt_u32_b32 v206, vcc_lo, v206
	v_bcnt_u32_b32 v206, vcc_hi, v206
	v_cmp_ge_u32_e32 vcc, v47, v3
	s_and_saveexec_b64 s[6:7], vcc
	s_cbranch_execz .LBB0_1715
	v_mbcnt_lo_u32_b32 v135, vcc_lo, v206
	v_mbcnt_hi_u32_b32 v135, vcc_hi, v135
	v_lshl_add_u32 v136, v135, 2, s76
	ds_write_b32 v136, v47
	v_add_u16_e32 v136, 0xa00, v134
	v_lshl_add_u32 v135, v135, 1, s0
	ds_write_b16 v135, v136
.LBB0_1715:
	s_or_b64 exec, exec, s[6:7]
	v_bcnt_u32_b32 v206, vcc_lo, v206
	v_bcnt_u32_b32 v206, vcc_hi, v206
	v_cmp_ge_u32_e32 vcc, v46, v3
	s_and_saveexec_b64 s[6:7], vcc
	s_cbranch_execz .LBB0_1717
	v_mbcnt_lo_u32_b32 v135, vcc_lo, v206
	v_mbcnt_hi_u32_b32 v135, vcc_hi, v135
	v_lshl_add_u32 v136, v135, 2, s76
	ds_write_b32 v136, v46
	v_add_u16_e32 v136, 0xa40, v134
	v_lshl_add_u32 v135, v135, 1, s0
	ds_write_b16 v135, v136
.LBB0_1717:
	s_or_b64 exec, exec, s[6:7]
	v_bcnt_u32_b32 v206, vcc_lo, v206
	v_bcnt_u32_b32 v206, vcc_hi, v206
	v_cmp_ge_u32_e32 vcc, v49, v3
	s_and_saveexec_b64 s[6:7], vcc
	s_cbranch_execz .LBB0_1719
	v_mbcnt_lo_u32_b32 v135, vcc_lo, v206
	v_mbcnt_hi_u32_b32 v135, vcc_hi, v135
	v_lshl_add_u32 v136, v135, 2, s76
	ds_write_b32 v136, v49
	v_add_u16_e32 v136, 0xa80, v134
	v_lshl_add_u32 v135, v135, 1, s0
	ds_write_b16 v135, v136
.LBB0_1719:
	s_or_b64 exec, exec, s[6:7]
	v_bcnt_u32_b32 v206, vcc_lo, v206
	v_bcnt_u32_b32 v206, vcc_hi, v206
	v_cmp_ge_u32_e32 vcc, v48, v3
	s_and_saveexec_b64 s[6:7], vcc
	s_cbranch_execz .LBB0_1721
	v_mbcnt_lo_u32_b32 v135, vcc_lo, v206
	v_mbcnt_hi_u32_b32 v135, vcc_hi, v135
	v_lshl_add_u32 v136, v135, 2, s76
	ds_write_b32 v136, v48
	v_add_u16_e32 v136, 0xac0, v134
	v_lshl_add_u32 v135, v135, 1, s0
	ds_write_b16 v135, v136
.LBB0_1721:
	s_or_b64 exec, exec, s[6:7]
	v_bcnt_u32_b32 v206, vcc_lo, v206
	v_bcnt_u32_b32 v206, vcc_hi, v206
	v_cmp_ge_u32_e32 vcc, v51, v3
	s_and_saveexec_b64 s[6:7], vcc
	s_cbranch_execz .LBB0_1723
	v_mbcnt_lo_u32_b32 v135, vcc_lo, v206
	v_mbcnt_hi_u32_b32 v135, vcc_hi, v135
	v_lshl_add_u32 v136, v135, 2, s76
	ds_write_b32 v136, v51
	v_add_u16_e32 v136, 0xb00, v134
	v_lshl_add_u32 v135, v135, 1, s0
	ds_write_b16 v135, v136
.LBB0_1723:
	s_or_b64 exec, exec, s[6:7]
	v_bcnt_u32_b32 v206, vcc_lo, v206
	v_bcnt_u32_b32 v206, vcc_hi, v206
	v_cmp_ge_u32_e32 vcc, v50, v3
	s_and_saveexec_b64 s[6:7], vcc
	s_cbranch_execz .LBB0_1725
	v_mbcnt_lo_u32_b32 v135, vcc_lo, v206
	v_mbcnt_hi_u32_b32 v135, vcc_hi, v135
	v_lshl_add_u32 v136, v135, 2, s76
	ds_write_b32 v136, v50
	v_add_u16_e32 v136, 0xb40, v134
	v_lshl_add_u32 v135, v135, 1, s0
	ds_write_b16 v135, v136
.LBB0_1725:
	s_or_b64 exec, exec, s[6:7]
	v_bcnt_u32_b32 v206, vcc_lo, v206
	v_bcnt_u32_b32 v206, vcc_hi, v206
	v_cmp_ge_u32_e32 vcc, v53, v3
	s_and_saveexec_b64 s[6:7], vcc
	s_cbranch_execz .LBB0_1727
	v_mbcnt_lo_u32_b32 v135, vcc_lo, v206
	v_mbcnt_hi_u32_b32 v135, vcc_hi, v135
	v_lshl_add_u32 v136, v135, 2, s76
	ds_write_b32 v136, v53
	v_add_u16_e32 v136, 0xb80, v134
	v_lshl_add_u32 v135, v135, 1, s0
	ds_write_b16 v135, v136
.LBB0_1727:
	s_or_b64 exec, exec, s[6:7]
	v_bcnt_u32_b32 v206, vcc_lo, v206
	v_bcnt_u32_b32 v206, vcc_hi, v206
	v_cmp_ge_u32_e32 vcc, v52, v3
	s_and_saveexec_b64 s[6:7], vcc
	s_cbranch_execz .LBB0_1729
	v_mbcnt_lo_u32_b32 v135, vcc_lo, v206
	v_mbcnt_hi_u32_b32 v135, vcc_hi, v135
	v_lshl_add_u32 v136, v135, 2, s76
	v_add_u16_e32 v134, 0xbc0, v134
	v_lshl_add_u32 v135, v135, 1, s0
	ds_write_b32 v136, v52
	ds_write_b16 v135, v134
.LBB0_1729:
	s_or_b64 exec, exec, s[6:7]
	v_bcnt_u32_b32 v206, vcc_lo, v206
	v_bcnt_u32_b32 v206, vcc_hi, v206
	s_andn2_b64 vcc, exec, s[64:65]
	s_cbranch_vccz .LBB0_1628

.LBB0_1731:
	v_mov_b32_e32 v134, v30
	v_cmp_ge_u32_e32 vcc, v71, v3
	s_and_saveexec_b64 s[6:7], vcc
	s_cbranch_execz .LBB0_1733
	v_mbcnt_lo_u32_b32 v135, vcc_lo, v206
	v_mbcnt_hi_u32_b32 v135, vcc_hi, v135
	v_lshl_add_u32 v136, v135, 2, s76
	ds_write_b32 v136, v71
	v_add_u16_e32 v136, 0x1000, v134
	v_lshl_add_u32 v135, v135, 1, s0
	ds_write_b16 v135, v136
.LBB0_1733:
	s_or_b64 exec, exec, s[6:7]
	v_bcnt_u32_b32 v206, vcc_lo, v206
	v_bcnt_u32_b32 v206, vcc_hi, v206
	v_cmp_ge_u32_e32 vcc, v70, v3
	s_and_saveexec_b64 s[6:7], vcc
	s_cbranch_execz .LBB0_1735
	v_mbcnt_lo_u32_b32 v135, vcc_lo, v206
	v_mbcnt_hi_u32_b32 v135, vcc_hi, v135
	v_lshl_add_u32 v136, v135, 2, s76
	ds_write_b32 v136, v70
	v_add_u16_e32 v136, 0x1040, v134
	v_lshl_add_u32 v135, v135, 1, s0
	ds_write_b16 v135, v136
.LBB0_1735:
	s_or_b64 exec, exec, s[6:7]
	v_bcnt_u32_b32 v206, vcc_lo, v206
	v_bcnt_u32_b32 v206, vcc_hi, v206
	v_cmp_ge_u32_e32 vcc, v73, v3
	s_and_saveexec_b64 s[6:7], vcc
	s_cbranch_execz .LBB0_1737
	v_mbcnt_lo_u32_b32 v135, vcc_lo, v206
	v_mbcnt_hi_u32_b32 v135, vcc_hi, v135
	v_lshl_add_u32 v136, v135, 2, s76
	ds_write_b32 v136, v73
	v_add_u16_e32 v136, 0x1080, v134
	v_lshl_add_u32 v135, v135, 1, s0
	ds_write_b16 v135, v136
.LBB0_1737:
	s_or_b64 exec, exec, s[6:7]
	v_bcnt_u32_b32 v206, vcc_lo, v206
	v_bcnt_u32_b32 v206, vcc_hi, v206
	v_cmp_ge_u32_e32 vcc, v72, v3
	s_and_saveexec_b64 s[6:7], vcc
	s_cbranch_execz .LBB0_1739
	v_mbcnt_lo_u32_b32 v135, vcc_lo, v206
	v_mbcnt_hi_u32_b32 v135, vcc_hi, v135
	v_lshl_add_u32 v136, v135, 2, s76
	ds_write_b32 v136, v72
	v_add_u16_e32 v136, 0x10c0, v134
	v_lshl_add_u32 v135, v135, 1, s0
	ds_write_b16 v135, v136
.LBB0_1739:
	s_or_b64 exec, exec, s[6:7]
	v_bcnt_u32_b32 v206, vcc_lo, v206
	v_bcnt_u32_b32 v206, vcc_hi, v206
	v_cmp_ge_u32_e32 vcc, v75, v3
	s_and_saveexec_b64 s[6:7], vcc
	s_cbranch_execz .LBB0_1741
	v_mbcnt_lo_u32_b32 v135, vcc_lo, v206
	v_mbcnt_hi_u32_b32 v135, vcc_hi, v135
	v_lshl_add_u32 v136, v135, 2, s76
	ds_write_b32 v136, v75
	v_add_u16_e32 v136, 0x1100, v134
	v_lshl_add_u32 v135, v135, 1, s0
	ds_write_b16 v135, v136
.LBB0_1741:
	s_or_b64 exec, exec, s[6:7]
	v_bcnt_u32_b32 v206, vcc_lo, v206
	v_bcnt_u32_b32 v206, vcc_hi, v206
	v_cmp_ge_u32_e32 vcc, v74, v3
	s_and_saveexec_b64 s[6:7], vcc
	s_cbranch_execz .LBB0_1743
	v_mbcnt_lo_u32_b32 v135, vcc_lo, v206
	v_mbcnt_hi_u32_b32 v135, vcc_hi, v135
	v_lshl_add_u32 v136, v135, 2, s76
	ds_write_b32 v136, v74
	v_add_u16_e32 v136, 0x1140, v134
	v_lshl_add_u32 v135, v135, 1, s0
	ds_write_b16 v135, v136
.LBB0_1743:
	s_or_b64 exec, exec, s[6:7]
	v_bcnt_u32_b32 v206, vcc_lo, v206
	v_bcnt_u32_b32 v206, vcc_hi, v206
	v_cmp_ge_u32_e32 vcc, v77, v3
	s_and_saveexec_b64 s[6:7], vcc
	s_cbranch_execz .LBB0_1745
	v_mbcnt_lo_u32_b32 v135, vcc_lo, v206
	v_mbcnt_hi_u32_b32 v135, vcc_hi, v135
	v_lshl_add_u32 v136, v135, 2, s76
	ds_write_b32 v136, v77
	v_add_u16_e32 v136, 0x1180, v134
	v_lshl_add_u32 v135, v135, 1, s0
	ds_write_b16 v135, v136
.LBB0_1745:
	s_or_b64 exec, exec, s[6:7]
	v_bcnt_u32_b32 v206, vcc_lo, v206
	v_bcnt_u32_b32 v206, vcc_hi, v206
	v_cmp_ge_u32_e32 vcc, v76, v3
	s_and_saveexec_b64 s[6:7], vcc
	s_cbranch_execz .LBB0_1747
	v_mbcnt_lo_u32_b32 v135, vcc_lo, v206
	v_mbcnt_hi_u32_b32 v135, vcc_hi, v135
	v_lshl_add_u32 v136, v135, 2, s76
	ds_write_b32 v136, v76
	v_add_u16_e32 v136, 0x11c0, v134
	v_lshl_add_u32 v135, v135, 1, s0
	ds_write_b16 v135, v136
.LBB0_1747:
	s_or_b64 exec, exec, s[6:7]
	v_bcnt_u32_b32 v206, vcc_lo, v206
	v_bcnt_u32_b32 v206, vcc_hi, v206
	v_cmp_ge_u32_e32 vcc, v79, v3
	s_and_saveexec_b64 s[6:7], vcc
	s_cbranch_execz .LBB0_1749
	v_mbcnt_lo_u32_b32 v135, vcc_lo, v206
	v_mbcnt_hi_u32_b32 v135, vcc_hi, v135
	v_lshl_add_u32 v136, v135, 2, s76
	ds_write_b32 v136, v79
	v_add_u16_e32 v136, 0x1200, v134
	v_lshl_add_u32 v135, v135, 1, s0
	ds_write_b16 v135, v136
.LBB0_1749:
	s_or_b64 exec, exec, s[6:7]
	v_bcnt_u32_b32 v206, vcc_lo, v206
	v_bcnt_u32_b32 v206, vcc_hi, v206
	v_cmp_ge_u32_e32 vcc, v78, v3
	s_and_saveexec_b64 s[6:7], vcc
	s_cbranch_execz .LBB0_1751
	v_mbcnt_lo_u32_b32 v135, vcc_lo, v206
	v_mbcnt_hi_u32_b32 v135, vcc_hi, v135
	v_lshl_add_u32 v136, v135, 2, s76
	ds_write_b32 v136, v78
	v_add_u16_e32 v136, 0x1240, v134
	v_lshl_add_u32 v135, v135, 1, s0
	ds_write_b16 v135, v136
.LBB0_1751:
	s_or_b64 exec, exec, s[6:7]
	v_bcnt_u32_b32 v206, vcc_lo, v206
	v_bcnt_u32_b32 v206, vcc_hi, v206
	v_cmp_ge_u32_e32 vcc, v81, v3
	s_and_saveexec_b64 s[6:7], vcc
	s_cbranch_execz .LBB0_1753
	v_mbcnt_lo_u32_b32 v135, vcc_lo, v206
	v_mbcnt_hi_u32_b32 v135, vcc_hi, v135
	v_lshl_add_u32 v136, v135, 2, s76
	ds_write_b32 v136, v81
	v_add_u16_e32 v136, 0x1280, v134
	v_lshl_add_u32 v135, v135, 1, s0
	ds_write_b16 v135, v136
.LBB0_1753:
	s_or_b64 exec, exec, s[6:7]
	v_bcnt_u32_b32 v206, vcc_lo, v206
	v_bcnt_u32_b32 v206, vcc_hi, v206
	v_cmp_ge_u32_e32 vcc, v80, v3
	s_and_saveexec_b64 s[6:7], vcc
	s_cbranch_execz .LBB0_1755
	v_mbcnt_lo_u32_b32 v135, vcc_lo, v206
	v_mbcnt_hi_u32_b32 v135, vcc_hi, v135
	v_lshl_add_u32 v136, v135, 2, s76
	ds_write_b32 v136, v80
	v_add_u16_e32 v136, 0x12c0, v134
	v_lshl_add_u32 v135, v135, 1, s0
	ds_write_b16 v135, v136
.LBB0_1755:
	s_or_b64 exec, exec, s[6:7]
	v_bcnt_u32_b32 v206, vcc_lo, v206
	v_bcnt_u32_b32 v206, vcc_hi, v206
	v_cmp_ge_u32_e32 vcc, v83, v3
	s_and_saveexec_b64 s[6:7], vcc
	s_cbranch_execz .LBB0_1757
	v_mbcnt_lo_u32_b32 v135, vcc_lo, v206
	v_mbcnt_hi_u32_b32 v135, vcc_hi, v135
	v_lshl_add_u32 v136, v135, 2, s76
	ds_write_b32 v136, v83
	v_add_u16_e32 v136, 0x1300, v134
	v_lshl_add_u32 v135, v135, 1, s0
	ds_write_b16 v135, v136
.LBB0_1757:
	s_or_b64 exec, exec, s[6:7]
	v_bcnt_u32_b32 v206, vcc_lo, v206
	v_bcnt_u32_b32 v206, vcc_hi, v206
	v_cmp_ge_u32_e32 vcc, v82, v3
	s_and_saveexec_b64 s[6:7], vcc
	s_cbranch_execz .LBB0_1759
	v_mbcnt_lo_u32_b32 v135, vcc_lo, v206
	v_mbcnt_hi_u32_b32 v135, vcc_hi, v135
	v_lshl_add_u32 v136, v135, 2, s76
	ds_write_b32 v136, v82
	v_add_u16_e32 v136, 0x1340, v134
	v_lshl_add_u32 v135, v135, 1, s0
	ds_write_b16 v135, v136
.LBB0_1759:
	s_or_b64 exec, exec, s[6:7]
	v_bcnt_u32_b32 v206, vcc_lo, v206
	v_bcnt_u32_b32 v206, vcc_hi, v206
	v_cmp_ge_u32_e32 vcc, v85, v3
	s_and_saveexec_b64 s[6:7], vcc
	s_cbranch_execz .LBB0_1761
	v_mbcnt_lo_u32_b32 v135, vcc_lo, v206
	v_mbcnt_hi_u32_b32 v135, vcc_hi, v135
	v_lshl_add_u32 v136, v135, 2, s76
	ds_write_b32 v136, v85
	v_add_u16_e32 v136, 0x1380, v134
	v_lshl_add_u32 v135, v135, 1, s0
	ds_write_b16 v135, v136
.LBB0_1761:
	s_or_b64 exec, exec, s[6:7]
	v_bcnt_u32_b32 v206, vcc_lo, v206
	v_bcnt_u32_b32 v206, vcc_hi, v206
	v_cmp_ge_u32_e32 vcc, v84, v3
	s_and_saveexec_b64 s[6:7], vcc
	s_cbranch_execz .LBB0_1763
	v_mbcnt_lo_u32_b32 v135, vcc_lo, v206
	v_mbcnt_hi_u32_b32 v135, vcc_hi, v135
	v_lshl_add_u32 v136, v135, 2, s76
	v_add_u16_e32 v134, 0x13c0, v134
	v_lshl_add_u32 v135, v135, 1, s0
	ds_write_b32 v136, v84
	ds_write_b16 v135, v134
.LBB0_1763:
	s_or_b64 exec, exec, s[6:7]
	v_bcnt_u32_b32 v206, vcc_lo, v206
	v_bcnt_u32_b32 v206, vcc_hi, v206
	s_andn2_b64 vcc, exec, s[60:61]
	s_cbranch_vccz .LBB0_1662

.LBB0_1765:
	v_mov_b32_e32 v134, v30
	v_cmp_ge_u32_e32 vcc, v103, v3
	s_and_saveexec_b64 s[6:7], vcc
	s_cbranch_execz .LBB0_1767
	v_mbcnt_lo_u32_b32 v135, vcc_lo, v206
	v_mbcnt_hi_u32_b32 v135, vcc_hi, v135
	v_lshl_add_u32 v136, v135, 2, s76
	ds_write_b32 v136, v103
	v_add_u16_e32 v136, 0x1800, v134
	v_lshl_add_u32 v135, v135, 1, s0
	ds_write_b16 v135, v136
.LBB0_1767:
	s_or_b64 exec, exec, s[6:7]
	v_bcnt_u32_b32 v206, vcc_lo, v206
	v_bcnt_u32_b32 v206, vcc_hi, v206
	v_cmp_ge_u32_e32 vcc, v102, v3
	s_and_saveexec_b64 s[6:7], vcc
	s_cbranch_execz .LBB0_1769
	v_mbcnt_lo_u32_b32 v135, vcc_lo, v206
	v_mbcnt_hi_u32_b32 v135, vcc_hi, v135
	v_lshl_add_u32 v136, v135, 2, s76
	ds_write_b32 v136, v102
	v_add_u16_e32 v136, 0x1840, v134
	v_lshl_add_u32 v135, v135, 1, s0
	ds_write_b16 v135, v136
.LBB0_1769:
	s_or_b64 exec, exec, s[6:7]
	v_bcnt_u32_b32 v206, vcc_lo, v206
	v_bcnt_u32_b32 v206, vcc_hi, v206
	v_cmp_ge_u32_e32 vcc, v105, v3
	s_and_saveexec_b64 s[6:7], vcc
	s_cbranch_execz .LBB0_1771
	v_mbcnt_lo_u32_b32 v135, vcc_lo, v206
	v_mbcnt_hi_u32_b32 v135, vcc_hi, v135
	v_lshl_add_u32 v136, v135, 2, s76
	ds_write_b32 v136, v105
	v_add_u16_e32 v136, 0x1880, v134
	v_lshl_add_u32 v135, v135, 1, s0
	ds_write_b16 v135, v136
.LBB0_1771:
	s_or_b64 exec, exec, s[6:7]
	v_bcnt_u32_b32 v206, vcc_lo, v206
	v_bcnt_u32_b32 v206, vcc_hi, v206
	v_cmp_ge_u32_e32 vcc, v104, v3
	s_and_saveexec_b64 s[6:7], vcc
	s_cbranch_execz .LBB0_1773
	v_mbcnt_lo_u32_b32 v135, vcc_lo, v206
	v_mbcnt_hi_u32_b32 v135, vcc_hi, v135
	v_lshl_add_u32 v136, v135, 2, s76
	ds_write_b32 v136, v104
	v_add_u16_e32 v136, 0x18c0, v134
	v_lshl_add_u32 v135, v135, 1, s0
	ds_write_b16 v135, v136
.LBB0_1773:
	s_or_b64 exec, exec, s[6:7]
	v_bcnt_u32_b32 v206, vcc_lo, v206
	v_bcnt_u32_b32 v206, vcc_hi, v206
	v_cmp_ge_u32_e32 vcc, v107, v3
	s_and_saveexec_b64 s[6:7], vcc
	s_cbranch_execz .LBB0_1775
	v_mbcnt_lo_u32_b32 v135, vcc_lo, v206
	v_mbcnt_hi_u32_b32 v135, vcc_hi, v135
	v_lshl_add_u32 v136, v135, 2, s76
	ds_write_b32 v136, v107
	v_add_u16_e32 v136, 0x1900, v134
	v_lshl_add_u32 v135, v135, 1, s0
	ds_write_b16 v135, v136
.LBB0_1775:
	s_or_b64 exec, exec, s[6:7]
	v_bcnt_u32_b32 v206, vcc_lo, v206
	v_bcnt_u32_b32 v206, vcc_hi, v206
	v_cmp_ge_u32_e32 vcc, v106, v3
	s_and_saveexec_b64 s[6:7], vcc
	s_cbranch_execz .LBB0_1777
	v_mbcnt_lo_u32_b32 v135, vcc_lo, v206
	v_mbcnt_hi_u32_b32 v135, vcc_hi, v135
	v_lshl_add_u32 v136, v135, 2, s76
	ds_write_b32 v136, v106
	v_add_u16_e32 v136, 0x1940, v134
	v_lshl_add_u32 v135, v135, 1, s0
	ds_write_b16 v135, v136
.LBB0_1777:
	s_or_b64 exec, exec, s[6:7]
	v_bcnt_u32_b32 v206, vcc_lo, v206
	v_bcnt_u32_b32 v206, vcc_hi, v206
	v_cmp_ge_u32_e32 vcc, v109, v3
	s_and_saveexec_b64 s[6:7], vcc
	s_cbranch_execz .LBB0_1779
	v_mbcnt_lo_u32_b32 v135, vcc_lo, v206
	v_mbcnt_hi_u32_b32 v135, vcc_hi, v135
	v_lshl_add_u32 v136, v135, 2, s76
	ds_write_b32 v136, v109
	v_add_u16_e32 v136, 0x1980, v134
	v_lshl_add_u32 v135, v135, 1, s0
	ds_write_b16 v135, v136
.LBB0_1779:
	s_or_b64 exec, exec, s[6:7]
	v_bcnt_u32_b32 v206, vcc_lo, v206
	v_bcnt_u32_b32 v206, vcc_hi, v206
	v_cmp_ge_u32_e32 vcc, v108, v3
	s_and_saveexec_b64 s[6:7], vcc
	s_cbranch_execz .LBB0_1781
	v_mbcnt_lo_u32_b32 v135, vcc_lo, v206
	v_mbcnt_hi_u32_b32 v135, vcc_hi, v135
	v_lshl_add_u32 v136, v135, 2, s76
	ds_write_b32 v136, v108
	v_add_u16_e32 v136, 0x19c0, v134
	v_lshl_add_u32 v135, v135, 1, s0
	ds_write_b16 v135, v136
.LBB0_1781:
	s_or_b64 exec, exec, s[6:7]
	v_bcnt_u32_b32 v206, vcc_lo, v206
	v_bcnt_u32_b32 v206, vcc_hi, v206
	v_cmp_ge_u32_e32 vcc, v111, v3
	s_and_saveexec_b64 s[6:7], vcc
	s_cbranch_execz .LBB0_1783
	v_mbcnt_lo_u32_b32 v135, vcc_lo, v206
	v_mbcnt_hi_u32_b32 v135, vcc_hi, v135
	v_lshl_add_u32 v136, v135, 2, s76
	ds_write_b32 v136, v111
	v_add_u16_e32 v136, 0x1a00, v134
	v_lshl_add_u32 v135, v135, 1, s0
	ds_write_b16 v135, v136
.LBB0_1783:
	s_or_b64 exec, exec, s[6:7]
	v_bcnt_u32_b32 v206, vcc_lo, v206
	v_bcnt_u32_b32 v206, vcc_hi, v206
	v_cmp_ge_u32_e32 vcc, v110, v3
	s_and_saveexec_b64 s[6:7], vcc
	s_cbranch_execz .LBB0_1785
	v_mbcnt_lo_u32_b32 v135, vcc_lo, v206
	v_mbcnt_hi_u32_b32 v135, vcc_hi, v135
	v_lshl_add_u32 v136, v135, 2, s76
	ds_write_b32 v136, v110
	v_add_u16_e32 v136, 0x1a40, v134
	v_lshl_add_u32 v135, v135, 1, s0
	ds_write_b16 v135, v136
.LBB0_1785:
	s_or_b64 exec, exec, s[6:7]
	v_bcnt_u32_b32 v206, vcc_lo, v206
	v_bcnt_u32_b32 v206, vcc_hi, v206
	v_cmp_ge_u32_e32 vcc, v113, v3
	s_and_saveexec_b64 s[6:7], vcc
	s_cbranch_execz .LBB0_1787
	v_mbcnt_lo_u32_b32 v135, vcc_lo, v206
	v_mbcnt_hi_u32_b32 v135, vcc_hi, v135
	v_lshl_add_u32 v136, v135, 2, s76
	ds_write_b32 v136, v113
	v_add_u16_e32 v136, 0x1a80, v134
	v_lshl_add_u32 v135, v135, 1, s0
	ds_write_b16 v135, v136
.LBB0_1787:
	s_or_b64 exec, exec, s[6:7]
	v_bcnt_u32_b32 v206, vcc_lo, v206
	v_bcnt_u32_b32 v206, vcc_hi, v206
	v_cmp_ge_u32_e32 vcc, v112, v3
	s_and_saveexec_b64 s[6:7], vcc
	s_cbranch_execz .LBB0_1789
	v_mbcnt_lo_u32_b32 v135, vcc_lo, v206
	v_mbcnt_hi_u32_b32 v135, vcc_hi, v135
	v_lshl_add_u32 v136, v135, 2, s76
	ds_write_b32 v136, v112
	v_add_u16_e32 v136, 0x1ac0, v134
	v_lshl_add_u32 v135, v135, 1, s0
	ds_write_b16 v135, v136
.LBB0_1789:
	s_or_b64 exec, exec, s[6:7]
	v_bcnt_u32_b32 v206, vcc_lo, v206
	v_bcnt_u32_b32 v206, vcc_hi, v206
	v_cmp_ge_u32_e32 vcc, v115, v3
	s_and_saveexec_b64 s[6:7], vcc
	s_cbranch_execz .LBB0_1791
	v_mbcnt_lo_u32_b32 v135, vcc_lo, v206
	v_mbcnt_hi_u32_b32 v135, vcc_hi, v135
	v_lshl_add_u32 v136, v135, 2, s76
	ds_write_b32 v136, v115
	v_add_u16_e32 v136, 0x1b00, v134
	v_lshl_add_u32 v135, v135, 1, s0
	ds_write_b16 v135, v136
.LBB0_1791:
	s_or_b64 exec, exec, s[6:7]
	v_bcnt_u32_b32 v206, vcc_lo, v206
	v_bcnt_u32_b32 v206, vcc_hi, v206
	v_cmp_ge_u32_e32 vcc, v114, v3
	s_and_saveexec_b64 s[6:7], vcc
	s_cbranch_execz .LBB0_1793
	v_mbcnt_lo_u32_b32 v135, vcc_lo, v206
	v_mbcnt_hi_u32_b32 v135, vcc_hi, v135
	v_lshl_add_u32 v136, v135, 2, s76
	ds_write_b32 v136, v114
	v_add_u16_e32 v136, 0x1b40, v134
	v_lshl_add_u32 v135, v135, 1, s0
	ds_write_b16 v135, v136
.LBB0_1793:
	s_or_b64 exec, exec, s[6:7]
	v_bcnt_u32_b32 v206, vcc_lo, v206
	v_bcnt_u32_b32 v206, vcc_hi, v206
	v_cmp_ge_u32_e32 vcc, v117, v3
	s_and_saveexec_b64 s[6:7], vcc
	s_cbranch_execz .LBB0_1795
	v_mbcnt_lo_u32_b32 v135, vcc_lo, v206
	v_mbcnt_hi_u32_b32 v135, vcc_hi, v135
	v_lshl_add_u32 v136, v135, 2, s76
	ds_write_b32 v136, v117
	v_add_u16_e32 v136, 0x1b80, v134
	v_lshl_add_u32 v135, v135, 1, s0
	ds_write_b16 v135, v136
.LBB0_1795:
	s_or_b64 exec, exec, s[6:7]
	v_bcnt_u32_b32 v206, vcc_lo, v206
	v_bcnt_u32_b32 v206, vcc_hi, v206
	v_cmp_ge_u32_e32 vcc, v116, v3
	s_and_saveexec_b64 s[6:7], vcc
	s_cbranch_execz .LBB0_1797
	v_mbcnt_lo_u32_b32 v135, vcc_lo, v206
	v_mbcnt_hi_u32_b32 v135, vcc_hi, v135
	v_lshl_add_u32 v136, v135, 2, s76
	v_add_u16_e32 v134, 0x1bc0, v134
	v_lshl_add_u32 v135, v135, 1, s0
	ds_write_b32 v136, v116
	ds_write_b16 v135, v134
.LBB0_1797:
	s_or_b64 exec, exec, s[6:7]
	v_bcnt_u32_b32 v206, vcc_lo, v206
	v_bcnt_u32_b32 v206, vcc_hi, v206
	s_andn2_b64 vcc, exec, s[56:57]
	s_cbranch_vccnz .LBB0_1831
.LBB0_1798:
	v_mov_b32_e32 v134, v30
	v_cmp_ge_u32_e32 vcc, v119, v3
	s_and_saveexec_b64 s[6:7], vcc
	s_cbranch_execz .LBB0_1800
	v_mbcnt_lo_u32_b32 v135, vcc_lo, v206
	v_mbcnt_hi_u32_b32 v135, vcc_hi, v135
	v_lshl_add_u32 v136, v135, 2, s76
	ds_write_b32 v136, v119
	v_add_u16_e32 v136, 0x1c00, v134
	v_lshl_add_u32 v135, v135, 1, s0
	ds_write_b16 v135, v136
.LBB0_1800:
	s_or_b64 exec, exec, s[6:7]
	v_bcnt_u32_b32 v206, vcc_lo, v206
	v_bcnt_u32_b32 v206, vcc_hi, v206
	v_cmp_ge_u32_e32 vcc, v118, v3
	s_and_saveexec_b64 s[6:7], vcc
	s_cbranch_execz .LBB0_1802
	v_mbcnt_lo_u32_b32 v135, vcc_lo, v206
	v_mbcnt_hi_u32_b32 v135, vcc_hi, v135
	v_lshl_add_u32 v136, v135, 2, s76
	ds_write_b32 v136, v118
	v_add_u16_e32 v136, 0x1c40, v134
	v_lshl_add_u32 v135, v135, 1, s0
	ds_write_b16 v135, v136
.LBB0_1802:
	s_or_b64 exec, exec, s[6:7]
	v_bcnt_u32_b32 v206, vcc_lo, v206
	v_bcnt_u32_b32 v206, vcc_hi, v206
	v_cmp_ge_u32_e32 vcc, v123, v3
	s_and_saveexec_b64 s[6:7], vcc
	s_cbranch_execz .LBB0_1804
	v_mbcnt_lo_u32_b32 v135, vcc_lo, v206
	v_mbcnt_hi_u32_b32 v135, vcc_hi, v135
	v_lshl_add_u32 v136, v135, 2, s76
	ds_write_b32 v136, v123
	v_add_u16_e32 v136, 0x1c80, v134
	v_lshl_add_u32 v135, v135, 1, s0
	ds_write_b16 v135, v136
.LBB0_1804:
	s_or_b64 exec, exec, s[6:7]
	v_bcnt_u32_b32 v206, vcc_lo, v206
	v_bcnt_u32_b32 v206, vcc_hi, v206
	v_cmp_ge_u32_e32 vcc, v120, v3
	s_and_saveexec_b64 s[6:7], vcc
	s_cbranch_execz .LBB0_1806
	v_mbcnt_lo_u32_b32 v135, vcc_lo, v206
	v_mbcnt_hi_u32_b32 v135, vcc_hi, v135
	v_lshl_add_u32 v136, v135, 2, s76
	ds_write_b32 v136, v120
	v_add_u16_e32 v136, 0x1cc0, v134
	v_lshl_add_u32 v135, v135, 1, s0
	ds_write_b16 v135, v136
.LBB0_1806:
	s_or_b64 exec, exec, s[6:7]
	v_bcnt_u32_b32 v206, vcc_lo, v206
	v_bcnt_u32_b32 v206, vcc_hi, v206
	v_cmp_ge_u32_e32 vcc, v125, v3
	s_and_saveexec_b64 s[6:7], vcc
	s_cbranch_execz .LBB0_1808
	v_mbcnt_lo_u32_b32 v135, vcc_lo, v206
	v_mbcnt_hi_u32_b32 v135, vcc_hi, v135
	v_lshl_add_u32 v136, v135, 2, s76
	ds_write_b32 v136, v125
	v_add_u16_e32 v136, 0x1d00, v134
	v_lshl_add_u32 v135, v135, 1, s0
	ds_write_b16 v135, v136
.LBB0_1808:
	s_or_b64 exec, exec, s[6:7]
	v_bcnt_u32_b32 v206, vcc_lo, v206
	v_bcnt_u32_b32 v206, vcc_hi, v206
	v_cmp_ge_u32_e32 vcc, v121, v3
	s_and_saveexec_b64 s[6:7], vcc
	s_cbranch_execz .LBB0_1810
	v_mbcnt_lo_u32_b32 v135, vcc_lo, v206
	v_mbcnt_hi_u32_b32 v135, vcc_hi, v135
	v_lshl_add_u32 v136, v135, 2, s76
	ds_write_b32 v136, v121
	v_add_u16_e32 v136, 0x1d40, v134
	v_lshl_add_u32 v135, v135, 1, s0
	ds_write_b16 v135, v136
.LBB0_1810:
	s_or_b64 exec, exec, s[6:7]
	v_bcnt_u32_b32 v206, vcc_lo, v206
	v_bcnt_u32_b32 v206, vcc_hi, v206
	v_cmp_ge_u32_e32 vcc, v127, v3
	s_and_saveexec_b64 s[6:7], vcc
	s_cbranch_execz .LBB0_1812
	v_mbcnt_lo_u32_b32 v135, vcc_lo, v206
	v_mbcnt_hi_u32_b32 v135, vcc_hi, v135
	v_lshl_add_u32 v136, v135, 2, s76
	ds_write_b32 v136, v127
	v_add_u16_e32 v136, 0x1d80, v134
	v_lshl_add_u32 v135, v135, 1, s0
	ds_write_b16 v135, v136
.LBB0_1812:
	s_or_b64 exec, exec, s[6:7]
	v_bcnt_u32_b32 v206, vcc_lo, v206
	v_bcnt_u32_b32 v206, vcc_hi, v206
	v_cmp_ge_u32_e32 vcc, v122, v3
	s_and_saveexec_b64 s[6:7], vcc
	s_cbranch_execz .LBB0_1814
	v_mbcnt_lo_u32_b32 v135, vcc_lo, v206
	v_mbcnt_hi_u32_b32 v135, vcc_hi, v135
	v_lshl_add_u32 v136, v135, 2, s76
	ds_write_b32 v136, v122
	v_add_u16_e32 v136, 0x1dc0, v134
	v_lshl_add_u32 v135, v135, 1, s0
	ds_write_b16 v135, v136
.LBB0_1814:
	s_or_b64 exec, exec, s[6:7]
	v_bcnt_u32_b32 v206, vcc_lo, v206
	v_bcnt_u32_b32 v206, vcc_hi, v206
	v_cmp_ge_u32_e32 vcc, v129, v3
	s_and_saveexec_b64 s[6:7], vcc
	s_cbranch_execz .LBB0_1816
	v_mbcnt_lo_u32_b32 v135, vcc_lo, v206
	v_mbcnt_hi_u32_b32 v135, vcc_hi, v135
	v_lshl_add_u32 v136, v135, 2, s76
	ds_write_b32 v136, v129
	v_add_u16_e32 v136, 0x1e00, v134
	v_lshl_add_u32 v135, v135, 1, s0
	ds_write_b16 v135, v136
.LBB0_1816:
	s_or_b64 exec, exec, s[6:7]
	v_bcnt_u32_b32 v206, vcc_lo, v206
	v_bcnt_u32_b32 v206, vcc_hi, v206
	v_cmp_ge_u32_e32 vcc, v124, v3
	s_and_saveexec_b64 s[6:7], vcc
	s_cbranch_execz .LBB0_1818
	v_mbcnt_lo_u32_b32 v135, vcc_lo, v206
	v_mbcnt_hi_u32_b32 v135, vcc_hi, v135
	v_lshl_add_u32 v136, v135, 2, s76
	ds_write_b32 v136, v124
	v_add_u16_e32 v136, 0x1e40, v134
	v_lshl_add_u32 v135, v135, 1, s0
	ds_write_b16 v135, v136
.LBB0_1818:
	s_or_b64 exec, exec, s[6:7]
	v_bcnt_u32_b32 v206, vcc_lo, v206
	v_bcnt_u32_b32 v206, vcc_hi, v206
	v_cmp_ge_u32_e32 vcc, v131, v3
	s_and_saveexec_b64 s[6:7], vcc
	s_cbranch_execz .LBB0_1820
	v_mbcnt_lo_u32_b32 v135, vcc_lo, v206
	v_mbcnt_hi_u32_b32 v135, vcc_hi, v135
	v_lshl_add_u32 v136, v135, 2, s76
	ds_write_b32 v136, v131
	v_add_u16_e32 v136, 0x1e80, v134
	v_lshl_add_u32 v135, v135, 1, s0
	ds_write_b16 v135, v136
.LBB0_1820:
	s_or_b64 exec, exec, s[6:7]
	v_bcnt_u32_b32 v206, vcc_lo, v206
	v_bcnt_u32_b32 v206, vcc_hi, v206
	v_cmp_ge_u32_e32 vcc, v126, v3
	s_and_saveexec_b64 s[6:7], vcc
	s_cbranch_execz .LBB0_1822
	v_mbcnt_lo_u32_b32 v135, vcc_lo, v206
	v_mbcnt_hi_u32_b32 v135, vcc_hi, v135
	v_lshl_add_u32 v136, v135, 2, s76
	ds_write_b32 v136, v126
	v_add_u16_e32 v136, 0x1ec0, v134
	v_lshl_add_u32 v135, v135, 1, s0
	ds_write_b16 v135, v136
.LBB0_1822:
	s_or_b64 exec, exec, s[6:7]
	v_bcnt_u32_b32 v206, vcc_lo, v206
	v_bcnt_u32_b32 v206, vcc_hi, v206
	v_cmp_ge_u32_e32 vcc, v132, v3
	s_and_saveexec_b64 s[6:7], vcc
	s_cbranch_execz .LBB0_1824
	v_mbcnt_lo_u32_b32 v135, vcc_lo, v206
	v_mbcnt_hi_u32_b32 v135, vcc_hi, v135
	v_lshl_add_u32 v136, v135, 2, s76
	ds_write_b32 v136, v132
	v_add_u16_e32 v136, 0x1f00, v134
	v_lshl_add_u32 v135, v135, 1, s0
	ds_write_b16 v135, v136
.LBB0_1824:
	s_or_b64 exec, exec, s[6:7]
	v_bcnt_u32_b32 v206, vcc_lo, v206
	v_bcnt_u32_b32 v206, vcc_hi, v206
	v_cmp_ge_u32_e32 vcc, v128, v3
	s_and_saveexec_b64 s[6:7], vcc
	s_cbranch_execz .LBB0_1826
	v_mbcnt_lo_u32_b32 v135, vcc_lo, v206
	v_mbcnt_hi_u32_b32 v135, vcc_hi, v135
	v_lshl_add_u32 v136, v135, 2, s76
	ds_write_b32 v136, v128
	v_add_u16_e32 v136, 0x1f40, v134
	v_lshl_add_u32 v135, v135, 1, s0
	ds_write_b16 v135, v136
.LBB0_1826:
	s_or_b64 exec, exec, s[6:7]
	v_bcnt_u32_b32 v206, vcc_lo, v206
	v_bcnt_u32_b32 v206, vcc_hi, v206
	v_cmp_ge_u32_e32 vcc, v133, v3
	s_and_saveexec_b64 s[6:7], vcc
	s_cbranch_execz .LBB0_1828
	v_mbcnt_lo_u32_b32 v135, vcc_lo, v206
	v_mbcnt_hi_u32_b32 v135, vcc_hi, v135
	v_lshl_add_u32 v136, v135, 2, s76
	ds_write_b32 v136, v133
	v_add_u16_e32 v136, 0x1f80, v134
	v_lshl_add_u32 v135, v135, 1, s0
	ds_write_b16 v135, v136
.LBB0_1828:
	s_or_b64 exec, exec, s[6:7]
	v_cmp_ge_u32_e64 s[6:7], v130, v3
	s_and_saveexec_b64 s[8:9], s[6:7]
	s_cbranch_execz .LBB0_1830
	v_bcnt_u32_b32 v206, vcc_lo, v206
	v_bcnt_u32_b32 v206, vcc_hi, v206
	v_mbcnt_lo_u32_b32 v3, s6, v206
	v_mbcnt_hi_u32_b32 v3, s7, v3
	v_lshl_add_u32 v135, v3, 2, s76
	v_add_u16_e32 v134, 0x1fc0, v134
	v_lshl_add_u32 v3, v3, 1, s0
	ds_write_b32 v135, v130
	ds_write_b16 v3, v134

.LBB0_3819:
	s_and_b64 vcc, exec, s[4:5]
	s_cbranch_vccz .LBB0_4090
	v_mov_b32_e32 v206, 0
	v_mov_b32_e32 v135, v30
	v_cmp_ne_u32_e32 vcc, 0, v134
	s_and_saveexec_b64 s[8:9], s[6:7]
	s_cbranch_execz .LBB0_3822
	v_mbcnt_lo_u32_b32 v134, vcc_lo, v206
	v_mbcnt_hi_u32_b32 v134, vcc_hi, v134
	v_lshl_add_u32 v136, v134, 2, s58
	v_lshl_add_u32 v134, v134, 1, s92
	ds_write_b32 v136, v19
	ds_write_b16 v134, v135
.LBB0_3822:
	s_or_b64 exec, exec, s[8:9]
	v_bcnt_u32_b32 v206, vcc_lo, v206
	v_bcnt_u32_b32 v206, vcc_hi, v206
	v_cmp_ge_u32_e32 vcc, v13, v3
	s_and_saveexec_b64 s[6:7], vcc
	s_cbranch_execz .LBB0_3824
	v_mbcnt_lo_u32_b32 v134, vcc_lo, v206
	v_mbcnt_hi_u32_b32 v134, vcc_hi, v134
	v_lshl_add_u32 v136, v134, 2, s58
	ds_write_b32 v136, v13
	v_add_u16_e32 v136, 64, v135
	v_lshl_add_u32 v134, v134, 1, s92
	ds_write_b16 v134, v136
.LBB0_3824:
	s_or_b64 exec, exec, s[6:7]
	v_bcnt_u32_b32 v206, vcc_lo, v206
	v_bcnt_u32_b32 v206, vcc_hi, v206
	v_cmp_ge_u32_e32 vcc, v20, v3
	s_and_saveexec_b64 s[6:7], vcc
	s_cbranch_execz .LBB0_3826
	v_mbcnt_lo_u32_b32 v134, vcc_lo, v206
	v_mbcnt_hi_u32_b32 v134, vcc_hi, v134
	v_lshl_add_u32 v136, v134, 2, s58
	ds_write_b32 v136, v20
	v_add_u16_e32 v136, 0x80, v135
	v_lshl_add_u32 v134, v134, 1, s92
	ds_write_b16 v134, v136
.LBB0_3826:
	s_or_b64 exec, exec, s[6:7]
	v_bcnt_u32_b32 v206, vcc_lo, v206
	v_bcnt_u32_b32 v206, vcc_hi, v206
	v_cmp_ge_u32_e32 vcc, v12, v3
	s_and_saveexec_b64 s[6:7], vcc
	s_cbranch_execz .LBB0_3828
	v_mbcnt_lo_u32_b32 v134, vcc_lo, v206
	v_mbcnt_hi_u32_b32 v134, vcc_hi, v134
	v_lshl_add_u32 v136, v134, 2, s58
	ds_write_b32 v136, v12
	v_add_u16_e32 v136, 0xc0, v135
	v_lshl_add_u32 v134, v134, 1, s92
	ds_write_b16 v134, v136
.LBB0_3828:
	s_or_b64 exec, exec, s[6:7]
	v_bcnt_u32_b32 v206, vcc_lo, v206
	v_bcnt_u32_b32 v206, vcc_hi, v206
	v_cmp_ge_u32_e32 vcc, v18, v3
	s_and_saveexec_b64 s[6:7], vcc
	s_cbranch_execz .LBB0_3830
	v_mbcnt_lo_u32_b32 v134, vcc_lo, v206
	v_mbcnt_hi_u32_b32 v134, vcc_hi, v134
	v_lshl_add_u32 v136, v134, 2, s58
	ds_write_b32 v136, v18
	v_add_u16_e32 v136, 0x100, v135
	v_lshl_add_u32 v134, v134, 1, s92
	ds_write_b16 v134, v136
.LBB0_3830:
	s_or_b64 exec, exec, s[6:7]
	v_bcnt_u32_b32 v206, vcc_lo, v206
	v_bcnt_u32_b32 v206, vcc_hi, v206
	v_cmp_ge_u32_e32 vcc, v10, v3
	s_and_saveexec_b64 s[6:7], vcc
	s_cbranch_execz .LBB0_3832
	v_mbcnt_lo_u32_b32 v134, vcc_lo, v206
	v_mbcnt_hi_u32_b32 v134, vcc_hi, v134
	v_lshl_add_u32 v136, v134, 2, s58
	ds_write_b32 v136, v10
	v_add_u16_e32 v136, 0x140, v135
	v_lshl_add_u32 v134, v134, 1, s92
	ds_write_b16 v134, v136
.LBB0_3832:
	s_or_b64 exec, exec, s[6:7]
	v_bcnt_u32_b32 v206, vcc_lo, v206
	v_bcnt_u32_b32 v206, vcc_hi, v206
	v_cmp_ge_u32_e32 vcc, v17, v3
	s_and_saveexec_b64 s[6:7], vcc
	s_cbranch_execz .LBB0_3834
	v_mbcnt_lo_u32_b32 v134, vcc_lo, v206
	v_mbcnt_hi_u32_b32 v134, vcc_hi, v134
	v_lshl_add_u32 v136, v134, 2, s58
	ds_write_b32 v136, v17
	v_add_u16_e32 v136, 0x180, v135
	v_lshl_add_u32 v134, v134, 1, s92
	ds_write_b16 v134, v136
.LBB0_3834:
	s_or_b64 exec, exec, s[6:7]
	v_bcnt_u32_b32 v206, vcc_lo, v206
	v_bcnt_u32_b32 v206, vcc_hi, v206
	v_cmp_ge_u32_e32 vcc, v9, v3
	s_and_saveexec_b64 s[6:7], vcc
	s_cbranch_execz .LBB0_3836
	v_mbcnt_lo_u32_b32 v134, vcc_lo, v206
	v_mbcnt_hi_u32_b32 v134, vcc_hi, v134
	v_lshl_add_u32 v136, v134, 2, s58
	ds_write_b32 v136, v9
	v_add_u16_e32 v136, 0x1c0, v135
	v_lshl_add_u32 v134, v134, 1, s92
	ds_write_b16 v134, v136
.LBB0_3836:
	s_or_b64 exec, exec, s[6:7]
	v_bcnt_u32_b32 v206, vcc_lo, v206
	v_bcnt_u32_b32 v206, vcc_hi, v206
	v_cmp_ge_u32_e32 vcc, v16, v3
	s_and_saveexec_b64 s[6:7], vcc
	s_cbranch_execz .LBB0_3838
	v_mbcnt_lo_u32_b32 v134, vcc_lo, v206
	v_mbcnt_hi_u32_b32 v134, vcc_hi, v134
	v_lshl_add_u32 v136, v134, 2, s58
	ds_write_b32 v136, v16
	v_add_u16_e32 v136, 0x200, v135
	v_lshl_add_u32 v134, v134, 1, s92
	ds_write_b16 v134, v136
.LBB0_3838:
	s_or_b64 exec, exec, s[6:7]
	v_bcnt_u32_b32 v206, vcc_lo, v206
	v_bcnt_u32_b32 v206, vcc_hi, v206
	v_cmp_ge_u32_e32 vcc, v8, v3
	s_and_saveexec_b64 s[6:7], vcc
	s_cbranch_execz .LBB0_3840
	v_mbcnt_lo_u32_b32 v134, vcc_lo, v206
	v_mbcnt_hi_u32_b32 v134, vcc_hi, v134
	v_lshl_add_u32 v136, v134, 2, s58
	ds_write_b32 v136, v8
	v_add_u16_e32 v136, 0x240, v135
	v_lshl_add_u32 v134, v134, 1, s92
	ds_write_b16 v134, v136
.LBB0_3840:
	s_or_b64 exec, exec, s[6:7]
	v_bcnt_u32_b32 v206, vcc_lo, v206
	v_bcnt_u32_b32 v206, vcc_hi, v206
	v_cmp_ge_u32_e32 vcc, v15, v3
	s_and_saveexec_b64 s[6:7], vcc
	s_cbranch_execz .LBB0_3842
	v_mbcnt_lo_u32_b32 v134, vcc_lo, v206
	v_mbcnt_hi_u32_b32 v134, vcc_hi, v134
	v_lshl_add_u32 v136, v134, 2, s58
	ds_write_b32 v136, v15
	v_add_u16_e32 v136, 0x280, v135
	v_lshl_add_u32 v134, v134, 1, s92
	ds_write_b16 v134, v136
.LBB0_3842:
	s_or_b64 exec, exec, s[6:7]
	v_bcnt_u32_b32 v206, vcc_lo, v206
	v_bcnt_u32_b32 v206, vcc_hi, v206
	v_cmp_ge_u32_e32 vcc, v7, v3
	s_and_saveexec_b64 s[6:7], vcc
	s_cbranch_execz .LBB0_3844
	v_mbcnt_lo_u32_b32 v134, vcc_lo, v206
	v_mbcnt_hi_u32_b32 v134, vcc_hi, v134
	v_lshl_add_u32 v136, v134, 2, s58
	ds_write_b32 v136, v7
	v_add_u16_e32 v136, 0x2c0, v135
	v_lshl_add_u32 v134, v134, 1, s92
	ds_write_b16 v134, v136
.LBB0_3844:
	s_or_b64 exec, exec, s[6:7]
	v_bcnt_u32_b32 v206, vcc_lo, v206
	v_bcnt_u32_b32 v206, vcc_hi, v206
	v_cmp_ge_u32_e32 vcc, v14, v3
	s_and_saveexec_b64 s[6:7], vcc
	s_cbranch_execz .LBB0_3846
	v_mbcnt_lo_u32_b32 v134, vcc_lo, v206
	v_mbcnt_hi_u32_b32 v134, vcc_hi, v134
	v_lshl_add_u32 v136, v134, 2, s58
	ds_write_b32 v136, v14
	v_add_u16_e32 v136, 0x300, v135
	v_lshl_add_u32 v134, v134, 1, s92
	ds_write_b16 v134, v136
.LBB0_3846:
	s_or_b64 exec, exec, s[6:7]
	v_bcnt_u32_b32 v206, vcc_lo, v206
	v_bcnt_u32_b32 v206, vcc_hi, v206
	v_cmp_ge_u32_e32 vcc, v5, v3
	s_and_saveexec_b64 s[6:7], vcc
	s_cbranch_execz .LBB0_3848
	v_mbcnt_lo_u32_b32 v134, vcc_lo, v206
	v_mbcnt_hi_u32_b32 v134, vcc_hi, v134
	v_lshl_add_u32 v136, v134, 2, s58
	ds_write_b32 v136, v5
	v_add_u16_e32 v136, 0x340, v135
	v_lshl_add_u32 v134, v134, 1, s92
	ds_write_b16 v134, v136
.LBB0_3848:
	s_or_b64 exec, exec, s[6:7]
	v_bcnt_u32_b32 v206, vcc_lo, v206
	v_bcnt_u32_b32 v206, vcc_hi, v206
	v_cmp_ge_u32_e32 vcc, v11, v3
	s_and_saveexec_b64 s[6:7], vcc
	s_cbranch_execz .LBB0_3850
	v_mbcnt_lo_u32_b32 v134, vcc_lo, v206
	v_mbcnt_hi_u32_b32 v134, vcc_hi, v134
	v_lshl_add_u32 v136, v134, 2, s58
	ds_write_b32 v136, v11
	v_add_u16_e32 v136, 0x380, v135
	v_lshl_add_u32 v134, v134, 1, s92
	ds_write_b16 v134, v136
.LBB0_3850:
	s_or_b64 exec, exec, s[6:7]
	v_bcnt_u32_b32 v206, vcc_lo, v206
	v_bcnt_u32_b32 v206, vcc_hi, v206
	v_cmp_ge_u32_e32 vcc, v4, v3
	s_and_saveexec_b64 s[6:7], vcc
	s_cbranch_execz .LBB0_3852
	v_mbcnt_lo_u32_b32 v134, vcc_lo, v206
	v_mbcnt_hi_u32_b32 v134, vcc_hi, v134
	v_lshl_add_u32 v136, v134, 2, s58
	v_add_u16_e32 v135, 0x3c0, v135
	v_lshl_add_u32 v134, v134, 1, s92
	ds_write_b32 v136, v4
	ds_write_b16 v134, v135
.LBB0_3852:
	s_or_b64 exec, exec, s[6:7]
	v_bcnt_u32_b32 v206, vcc_lo, v206
	v_bcnt_u32_b32 v206, vcc_hi, v206
	s_andn2_b64 vcc, exec, s[68:69]
	s_cbranch_vccnz .LBB0_3955
	v_mov_b32_e32 v134, v30
	v_cmp_ge_u32_e32 vcc, v22, v3
	s_and_saveexec_b64 s[6:7], vcc
	s_cbranch_execz .LBB0_3855
	v_mbcnt_lo_u32_b32 v135, vcc_lo, v206
	v_mbcnt_hi_u32_b32 v135, vcc_hi, v135
	v_lshl_add_u32 v136, v135, 2, s58
	ds_write_b32 v136, v22
	v_add_u16_e32 v136, 0x400, v134
	v_lshl_add_u32 v135, v135, 1, s92
	ds_write_b16 v135, v136
.LBB0_3855:
	s_or_b64 exec, exec, s[6:7]
	v_bcnt_u32_b32 v206, vcc_lo, v206
	v_bcnt_u32_b32 v206, vcc_hi, v206
	v_cmp_ge_u32_e32 vcc, v21, v3
	s_and_saveexec_b64 s[6:7], vcc
	s_cbranch_execz .LBB0_3857
	v_mbcnt_lo_u32_b32 v135, vcc_lo, v206
	v_mbcnt_hi_u32_b32 v135, vcc_hi, v135
	v_lshl_add_u32 v136, v135, 2, s58
	ds_write_b32 v136, v21
	v_add_u16_e32 v136, 0x440, v134
	v_lshl_add_u32 v135, v135, 1, s92
	ds_write_b16 v135, v136
.LBB0_3857:
	s_or_b64 exec, exec, s[6:7]
	v_bcnt_u32_b32 v206, vcc_lo, v206
	v_bcnt_u32_b32 v206, vcc_hi, v206
	v_cmp_ge_u32_e32 vcc, v24, v3
	s_and_saveexec_b64 s[6:7], vcc
	s_cbranch_execz .LBB0_3859
	v_mbcnt_lo_u32_b32 v135, vcc_lo, v206
	v_mbcnt_hi_u32_b32 v135, vcc_hi, v135
	v_lshl_add_u32 v136, v135, 2, s58
	ds_write_b32 v136, v24
	v_add_u16_e32 v136, 0x480, v134
	v_lshl_add_u32 v135, v135, 1, s92
	ds_write_b16 v135, v136
.LBB0_3859:
	s_or_b64 exec, exec, s[6:7]
	v_bcnt_u32_b32 v206, vcc_lo, v206
	v_bcnt_u32_b32 v206, vcc_hi, v206
	v_cmp_ge_u32_e32 vcc, v23, v3
	s_and_saveexec_b64 s[6:7], vcc
	s_cbranch_execz .LBB0_3861
	v_mbcnt_lo_u32_b32 v135, vcc_lo, v206
	v_mbcnt_hi_u32_b32 v135, vcc_hi, v135
	v_lshl_add_u32 v136, v135, 2, s58
	ds_write_b32 v136, v23
	v_add_u16_e32 v136, 0x4c0, v134
	v_lshl_add_u32 v135, v135, 1, s92
	ds_write_b16 v135, v136
.LBB0_3861:
	s_or_b64 exec, exec, s[6:7]
	v_bcnt_u32_b32 v206, vcc_lo, v206
	v_bcnt_u32_b32 v206, vcc_hi, v206
	v_cmp_ge_u32_e32 vcc, v26, v3
	s_and_saveexec_b64 s[6:7], vcc
	s_cbranch_execz .LBB0_3863
	v_mbcnt_lo_u32_b32 v135, vcc_lo, v206
	v_mbcnt_hi_u32_b32 v135, vcc_hi, v135
	v_lshl_add_u32 v136, v135, 2, s58
	ds_write_b32 v136, v26
	v_add_u16_e32 v136, 0x500, v134
	v_lshl_add_u32 v135, v135, 1, s92
	ds_write_b16 v135, v136
.LBB0_3863:
	s_or_b64 exec, exec, s[6:7]
	v_bcnt_u32_b32 v206, vcc_lo, v206
	v_bcnt_u32_b32 v206, vcc_hi, v206
	v_cmp_ge_u32_e32 vcc, v25, v3
	s_and_saveexec_b64 s[6:7], vcc
	s_cbranch_execz .LBB0_3865
	v_mbcnt_lo_u32_b32 v135, vcc_lo, v206
	v_mbcnt_hi_u32_b32 v135, vcc_hi, v135
	v_lshl_add_u32 v136, v135, 2, s58
	ds_write_b32 v136, v25
	v_add_u16_e32 v136, 0x540, v134
	v_lshl_add_u32 v135, v135, 1, s92
	ds_write_b16 v135, v136
.LBB0_3865:
	s_or_b64 exec, exec, s[6:7]
	v_bcnt_u32_b32 v206, vcc_lo, v206
	v_bcnt_u32_b32 v206, vcc_hi, v206
	v_cmp_ge_u32_e32 vcc, v28, v3
	s_and_saveexec_b64 s[6:7], vcc
	s_cbranch_execz .LBB0_3867
	v_mbcnt_lo_u32_b32 v135, vcc_lo, v206
	v_mbcnt_hi_u32_b32 v135, vcc_hi, v135
	v_lshl_add_u32 v136, v135, 2, s58
	ds_write_b32 v136, v28
	v_add_u16_e32 v136, 0x580, v134
	v_lshl_add_u32 v135, v135, 1, s92
	ds_write_b16 v135, v136
.LBB0_3867:
	s_or_b64 exec, exec, s[6:7]
	v_bcnt_u32_b32 v206, vcc_lo, v206
	v_bcnt_u32_b32 v206, vcc_hi, v206
	v_cmp_ge_u32_e32 vcc, v27, v3
	s_and_saveexec_b64 s[6:7], vcc
	s_cbranch_execz .LBB0_3869
	v_mbcnt_lo_u32_b32 v135, vcc_lo, v206
	v_mbcnt_hi_u32_b32 v135, vcc_hi, v135
	v_lshl_add_u32 v136, v135, 2, s58
	ds_write_b32 v136, v27
	v_add_u16_e32 v136, 0x5c0, v134
	v_lshl_add_u32 v135, v135, 1, s92
	ds_write_b16 v135, v136
.LBB0_3869:
	s_or_b64 exec, exec, s[6:7]
	v_bcnt_u32_b32 v206, vcc_lo, v206
	v_bcnt_u32_b32 v206, vcc_hi, v206
	v_cmp_ge_u32_e32 vcc, v31, v3
	s_and_saveexec_b64 s[6:7], vcc
	s_cbranch_execz .LBB0_3871
	v_mbcnt_lo_u32_b32 v135, vcc_lo, v206
	v_mbcnt_hi_u32_b32 v135, vcc_hi, v135
	v_lshl_add_u32 v136, v135, 2, s58
	ds_write_b32 v136, v31
	v_add_u16_e32 v136, 0x600, v134
	v_lshl_add_u32 v135, v135, 1, s92
	ds_write_b16 v135, v136
.LBB0_3871:
	s_or_b64 exec, exec, s[6:7]
	v_bcnt_u32_b32 v206, vcc_lo, v206
	v_bcnt_u32_b32 v206, vcc_hi, v206
	v_cmp_ge_u32_e32 vcc, v29, v3
	s_and_saveexec_b64 s[6:7], vcc
	s_cbranch_execz .LBB0_3873
	v_mbcnt_lo_u32_b32 v135, vcc_lo, v206
	v_mbcnt_hi_u32_b32 v135, vcc_hi, v135
	v_lshl_add_u32 v136, v135, 2, s58
	ds_write_b32 v136, v29
	v_add_u16_e32 v136, 0x640, v134
	v_lshl_add_u32 v135, v135, 1, s92
	ds_write_b16 v135, v136
.LBB0_3873:
	s_or_b64 exec, exec, s[6:7]
	v_bcnt_u32_b32 v206, vcc_lo, v206
	v_bcnt_u32_b32 v206, vcc_hi, v206
	v_cmp_ge_u32_e32 vcc, v33, v3
	s_and_saveexec_b64 s[6:7], vcc
	s_cbranch_execz .LBB0_3875
	v_mbcnt_lo_u32_b32 v135, vcc_lo, v206
	v_mbcnt_hi_u32_b32 v135, vcc_hi, v135
	v_lshl_add_u32 v136, v135, 2, s58
	ds_write_b32 v136, v33
	v_add_u16_e32 v136, 0x680, v134
	v_lshl_add_u32 v135, v135, 1, s92
	ds_write_b16 v135, v136
.LBB0_3875:
	s_or_b64 exec, exec, s[6:7]
	v_bcnt_u32_b32 v206, vcc_lo, v206
	v_bcnt_u32_b32 v206, vcc_hi, v206
	v_cmp_ge_u32_e32 vcc, v32, v3
	s_and_saveexec_b64 s[6:7], vcc
	s_cbranch_execz .LBB0_3877
	v_mbcnt_lo_u32_b32 v135, vcc_lo, v206
	v_mbcnt_hi_u32_b32 v135, vcc_hi, v135
	v_lshl_add_u32 v136, v135, 2, s58
	ds_write_b32 v136, v32
	v_add_u16_e32 v136, 0x6c0, v134
	v_lshl_add_u32 v135, v135, 1, s92
	ds_write_b16 v135, v136
.LBB0_3877:
	s_or_b64 exec, exec, s[6:7]
	v_bcnt_u32_b32 v206, vcc_lo, v206
	v_bcnt_u32_b32 v206, vcc_hi, v206
	v_cmp_ge_u32_e32 vcc, v35, v3
	s_and_saveexec_b64 s[6:7], vcc
	s_cbranch_execz .LBB0_3879
	v_mbcnt_lo_u32_b32 v135, vcc_lo, v206
	v_mbcnt_hi_u32_b32 v135, vcc_hi, v135
	v_lshl_add_u32 v136, v135, 2, s58
	ds_write_b32 v136, v35
	v_add_u16_e32 v136, 0x700, v134
	v_lshl_add_u32 v135, v135, 1, s92
	ds_write_b16 v135, v136
.LBB0_3879:
	s_or_b64 exec, exec, s[6:7]
	v_bcnt_u32_b32 v206, vcc_lo, v206
	v_bcnt_u32_b32 v206, vcc_hi, v206
	v_cmp_ge_u32_e32 vcc, v34, v3
	s_and_saveexec_b64 s[6:7], vcc
	s_cbranch_execz .LBB0_3881
	v_mbcnt_lo_u32_b32 v135, vcc_lo, v206
	v_mbcnt_hi_u32_b32 v135, vcc_hi, v135
	v_lshl_add_u32 v136, v135, 2, s58
	ds_write_b32 v136, v34
	v_add_u16_e32 v136, 0x740, v134
	v_lshl_add_u32 v135, v135, 1, s92
	ds_write_b16 v135, v136
.LBB0_3881:
	s_or_b64 exec, exec, s[6:7]
	v_bcnt_u32_b32 v206, vcc_lo, v206
	v_bcnt_u32_b32 v206, vcc_hi, v206
	v_cmp_ge_u32_e32 vcc, v37, v3
	s_and_saveexec_b64 s[6:7], vcc
	s_cbranch_execz .LBB0_3883
	v_mbcnt_lo_u32_b32 v135, vcc_lo, v206
	v_mbcnt_hi_u32_b32 v135, vcc_hi, v135
	v_lshl_add_u32 v136, v135, 2, s58
	ds_write_b32 v136, v37
	v_add_u16_e32 v136, 0x780, v134
	v_lshl_add_u32 v135, v135, 1, s92
	ds_write_b16 v135, v136
.LBB0_3883:
	s_or_b64 exec, exec, s[6:7]
	v_bcnt_u32_b32 v206, vcc_lo, v206
	v_bcnt_u32_b32 v206, vcc_hi, v206
	v_cmp_ge_u32_e32 vcc, v36, v3
	s_and_saveexec_b64 s[6:7], vcc
	s_cbranch_execz .LBB0_3885
	v_mbcnt_lo_u32_b32 v135, vcc_lo, v206
	v_mbcnt_hi_u32_b32 v135, vcc_hi, v135
	v_lshl_add_u32 v136, v135, 2, s58
	v_add_u16_e32 v134, 0x7c0, v134
	v_lshl_add_u32 v135, v135, 1, s92
	ds_write_b32 v136, v36
	ds_write_b16 v135, v134
.LBB0_3885:
	s_or_b64 exec, exec, s[6:7]
	v_bcnt_u32_b32 v206, vcc_lo, v206
	v_bcnt_u32_b32 v206, vcc_hi, v206
	s_andn2_b64 vcc, exec, s[54:55]
	s_cbranch_vccz .LBB0_3956

.LBB0_3887:
	v_mov_b32_e32 v134, v30
	v_cmp_ge_u32_e32 vcc, v55, v3
	s_and_saveexec_b64 s[6:7], vcc
	s_cbranch_execz .LBB0_3889
	v_mbcnt_lo_u32_b32 v135, vcc_lo, v206
	v_mbcnt_hi_u32_b32 v135, vcc_hi, v135
	v_lshl_add_u32 v136, v135, 2, s58
	ds_write_b32 v136, v55
	v_add_u16_e32 v136, 0xc00, v134
	v_lshl_add_u32 v135, v135, 1, s92
	ds_write_b16 v135, v136
.LBB0_3889:
	s_or_b64 exec, exec, s[6:7]
	v_bcnt_u32_b32 v206, vcc_lo, v206
	v_bcnt_u32_b32 v206, vcc_hi, v206
	v_cmp_ge_u32_e32 vcc, v54, v3
	s_and_saveexec_b64 s[6:7], vcc
	s_cbranch_execz .LBB0_3891
	v_mbcnt_lo_u32_b32 v135, vcc_lo, v206
	v_mbcnt_hi_u32_b32 v135, vcc_hi, v135
	v_lshl_add_u32 v136, v135, 2, s58
	ds_write_b32 v136, v54
	v_add_u16_e32 v136, 0xc40, v134
	v_lshl_add_u32 v135, v135, 1, s92
	ds_write_b16 v135, v136
.LBB0_3891:
	s_or_b64 exec, exec, s[6:7]
	v_bcnt_u32_b32 v206, vcc_lo, v206
	v_bcnt_u32_b32 v206, vcc_hi, v206
	v_cmp_ge_u32_e32 vcc, v57, v3
	s_and_saveexec_b64 s[6:7], vcc
	s_cbranch_execz .LBB0_3893
	v_mbcnt_lo_u32_b32 v135, vcc_lo, v206
	v_mbcnt_hi_u32_b32 v135, vcc_hi, v135
	v_lshl_add_u32 v136, v135, 2, s58
	ds_write_b32 v136, v57
	v_add_u16_e32 v136, 0xc80, v134
	v_lshl_add_u32 v135, v135, 1, s92
	ds_write_b16 v135, v136
.LBB0_3893:
	s_or_b64 exec, exec, s[6:7]
	v_bcnt_u32_b32 v206, vcc_lo, v206
	v_bcnt_u32_b32 v206, vcc_hi, v206
	v_cmp_ge_u32_e32 vcc, v56, v3
	s_and_saveexec_b64 s[6:7], vcc
	s_cbranch_execz .LBB0_3895
	v_mbcnt_lo_u32_b32 v135, vcc_lo, v206
	v_mbcnt_hi_u32_b32 v135, vcc_hi, v135
	v_lshl_add_u32 v136, v135, 2, s58
	ds_write_b32 v136, v56
	v_add_u16_e32 v136, 0xcc0, v134
	v_lshl_add_u32 v135, v135, 1, s92
	ds_write_b16 v135, v136
.LBB0_3895:
	s_or_b64 exec, exec, s[6:7]
	v_bcnt_u32_b32 v206, vcc_lo, v206
	v_bcnt_u32_b32 v206, vcc_hi, v206
	v_cmp_ge_u32_e32 vcc, v59, v3
	s_and_saveexec_b64 s[6:7], vcc
	s_cbranch_execz .LBB0_3897
	v_mbcnt_lo_u32_b32 v135, vcc_lo, v206
	v_mbcnt_hi_u32_b32 v135, vcc_hi, v135
	v_lshl_add_u32 v136, v135, 2, s58
	ds_write_b32 v136, v59
	v_add_u16_e32 v136, 0xd00, v134
	v_lshl_add_u32 v135, v135, 1, s92
	ds_write_b16 v135, v136
.LBB0_3897:
	s_or_b64 exec, exec, s[6:7]
	v_bcnt_u32_b32 v206, vcc_lo, v206
	v_bcnt_u32_b32 v206, vcc_hi, v206
	v_cmp_ge_u32_e32 vcc, v58, v3
	s_and_saveexec_b64 s[6:7], vcc
	s_cbranch_execz .LBB0_3899
	v_mbcnt_lo_u32_b32 v135, vcc_lo, v206
	v_mbcnt_hi_u32_b32 v135, vcc_hi, v135
	v_lshl_add_u32 v136, v135, 2, s58
	ds_write_b32 v136, v58
	v_add_u16_e32 v136, 0xd40, v134
	v_lshl_add_u32 v135, v135, 1, s92
	ds_write_b16 v135, v136
.LBB0_3899:
	s_or_b64 exec, exec, s[6:7]
	v_bcnt_u32_b32 v206, vcc_lo, v206
	v_bcnt_u32_b32 v206, vcc_hi, v206
	v_cmp_ge_u32_e32 vcc, v61, v3
	s_and_saveexec_b64 s[6:7], vcc
	s_cbranch_execz .LBB0_3901
	v_mbcnt_lo_u32_b32 v135, vcc_lo, v206
	v_mbcnt_hi_u32_b32 v135, vcc_hi, v135
	v_lshl_add_u32 v136, v135, 2, s58
	ds_write_b32 v136, v61
	v_add_u16_e32 v136, 0xd80, v134
	v_lshl_add_u32 v135, v135, 1, s92
	ds_write_b16 v135, v136
.LBB0_3901:
	s_or_b64 exec, exec, s[6:7]
	v_bcnt_u32_b32 v206, vcc_lo, v206
	v_bcnt_u32_b32 v206, vcc_hi, v206
	v_cmp_ge_u32_e32 vcc, v60, v3
	s_and_saveexec_b64 s[6:7], vcc
	s_cbranch_execz .LBB0_3903
	v_mbcnt_lo_u32_b32 v135, vcc_lo, v206
	v_mbcnt_hi_u32_b32 v135, vcc_hi, v135
	v_lshl_add_u32 v136, v135, 2, s58
	ds_write_b32 v136, v60
	v_add_u16_e32 v136, 0xdc0, v134
	v_lshl_add_u32 v135, v135, 1, s92
	ds_write_b16 v135, v136
.LBB0_3903:
	s_or_b64 exec, exec, s[6:7]
	v_bcnt_u32_b32 v206, vcc_lo, v206
	v_bcnt_u32_b32 v206, vcc_hi, v206
	v_cmp_ge_u32_e32 vcc, v63, v3
	s_and_saveexec_b64 s[6:7], vcc
	s_cbranch_execz .LBB0_3905
	v_mbcnt_lo_u32_b32 v135, vcc_lo, v206
	v_mbcnt_hi_u32_b32 v135, vcc_hi, v135
	v_lshl_add_u32 v136, v135, 2, s58
	ds_write_b32 v136, v63
	v_add_u16_e32 v136, 0xe00, v134
	v_lshl_add_u32 v135, v135, 1, s92
	ds_write_b16 v135, v136
.LBB0_3905:
	s_or_b64 exec, exec, s[6:7]
	v_bcnt_u32_b32 v206, vcc_lo, v206
	v_bcnt_u32_b32 v206, vcc_hi, v206
	v_cmp_ge_u32_e32 vcc, v62, v3
	s_and_saveexec_b64 s[6:7], vcc
	s_cbranch_execz .LBB0_3907
	v_mbcnt_lo_u32_b32 v135, vcc_lo, v206
	v_mbcnt_hi_u32_b32 v135, vcc_hi, v135
	v_lshl_add_u32 v136, v135, 2, s58
	ds_write_b32 v136, v62
	v_add_u16_e32 v136, 0xe40, v134
	v_lshl_add_u32 v135, v135, 1, s92
	ds_write_b16 v135, v136
.LBB0_3907:
	s_or_b64 exec, exec, s[6:7]
	v_bcnt_u32_b32 v206, vcc_lo, v206
	v_bcnt_u32_b32 v206, vcc_hi, v206
	v_cmp_ge_u32_e32 vcc, v65, v3
	s_and_saveexec_b64 s[6:7], vcc
	s_cbranch_execz .LBB0_3909
	v_mbcnt_lo_u32_b32 v135, vcc_lo, v206
	v_mbcnt_hi_u32_b32 v135, vcc_hi, v135
	v_lshl_add_u32 v136, v135, 2, s58
	ds_write_b32 v136, v65
	v_add_u16_e32 v136, 0xe80, v134
	v_lshl_add_u32 v135, v135, 1, s92
	ds_write_b16 v135, v136
.LBB0_3909:
	s_or_b64 exec, exec, s[6:7]
	v_bcnt_u32_b32 v206, vcc_lo, v206
	v_bcnt_u32_b32 v206, vcc_hi, v206
	v_cmp_ge_u32_e32 vcc, v64, v3
	s_and_saveexec_b64 s[6:7], vcc
	s_cbranch_execz .LBB0_3911
	v_mbcnt_lo_u32_b32 v135, vcc_lo, v206
	v_mbcnt_hi_u32_b32 v135, vcc_hi, v135
	v_lshl_add_u32 v136, v135, 2, s58
	ds_write_b32 v136, v64
	v_add_u16_e32 v136, 0xec0, v134
	v_lshl_add_u32 v135, v135, 1, s92
	ds_write_b16 v135, v136
.LBB0_3911:
	s_or_b64 exec, exec, s[6:7]
	v_bcnt_u32_b32 v206, vcc_lo, v206
	v_bcnt_u32_b32 v206, vcc_hi, v206
	v_cmp_ge_u32_e32 vcc, v67, v3
	s_and_saveexec_b64 s[6:7], vcc
	s_cbranch_execz .LBB0_3913
	v_mbcnt_lo_u32_b32 v135, vcc_lo, v206
	v_mbcnt_hi_u32_b32 v135, vcc_hi, v135
	v_lshl_add_u32 v136, v135, 2, s58
	ds_write_b32 v136, v67
	v_add_u16_e32 v136, 0xf00, v134
	v_lshl_add_u32 v135, v135, 1, s92
	ds_write_b16 v135, v136
.LBB0_3913:
	s_or_b64 exec, exec, s[6:7]
	v_bcnt_u32_b32 v206, vcc_lo, v206
	v_bcnt_u32_b32 v206, vcc_hi, v206
	v_cmp_ge_u32_e32 vcc, v66, v3
	s_and_saveexec_b64 s[6:7], vcc
	s_cbranch_execz .LBB0_3915
	v_mbcnt_lo_u32_b32 v135, vcc_lo, v206
	v_mbcnt_hi_u32_b32 v135, vcc_hi, v135
	v_lshl_add_u32 v136, v135, 2, s58
	ds_write_b32 v136, v66
	v_add_u16_e32 v136, 0xf40, v134
	v_lshl_add_u32 v135, v135, 1, s92
	ds_write_b16 v135, v136
.LBB0_3915:
	s_or_b64 exec, exec, s[6:7]
	v_bcnt_u32_b32 v206, vcc_lo, v206
	v_bcnt_u32_b32 v206, vcc_hi, v206
	v_cmp_ge_u32_e32 vcc, v69, v3
	s_and_saveexec_b64 s[6:7], vcc
	s_cbranch_execz .LBB0_3917
	v_mbcnt_lo_u32_b32 v135, vcc_lo, v206
	v_mbcnt_hi_u32_b32 v135, vcc_hi, v135
	v_lshl_add_u32 v136, v135, 2, s58
	ds_write_b32 v136, v69
	v_add_u16_e32 v136, 0xf80, v134
	v_lshl_add_u32 v135, v135, 1, s92
	ds_write_b16 v135, v136
.LBB0_3917:
	s_or_b64 exec, exec, s[6:7]
	v_bcnt_u32_b32 v206, vcc_lo, v206
	v_bcnt_u32_b32 v206, vcc_hi, v206
	v_cmp_ge_u32_e32 vcc, v68, v3
	s_and_saveexec_b64 s[6:7], vcc
	s_cbranch_execz .LBB0_3919
	v_mbcnt_lo_u32_b32 v135, vcc_lo, v206
	v_mbcnt_hi_u32_b32 v135, vcc_hi, v135
	v_lshl_add_u32 v136, v135, 2, s58
	v_add_u16_e32 v134, 0xfc0, v134
	v_lshl_add_u32 v135, v135, 1, s92
	ds_write_b32 v136, v68
	ds_write_b16 v135, v134
.LBB0_3919:
	s_or_b64 exec, exec, s[6:7]
	v_bcnt_u32_b32 v206, vcc_lo, v206
	v_bcnt_u32_b32 v206, vcc_hi, v206
	s_andn2_b64 vcc, exec, s[96:97]
	s_cbranch_vccz .LBB0_3990

.LBB0_3921:
	v_mov_b32_e32 v134, v30
	v_cmp_ge_u32_e32 vcc, v87, v3
	s_and_saveexec_b64 s[6:7], vcc
	s_cbranch_execz .LBB0_3923
	v_mbcnt_lo_u32_b32 v135, vcc_lo, v206
	v_mbcnt_hi_u32_b32 v135, vcc_hi, v135
	v_lshl_add_u32 v136, v135, 2, s58
	ds_write_b32 v136, v87
	v_add_u16_e32 v136, 0x1400, v134
	v_lshl_add_u32 v135, v135, 1, s92
	ds_write_b16 v135, v136
.LBB0_3923:
	s_or_b64 exec, exec, s[6:7]
	v_bcnt_u32_b32 v206, vcc_lo, v206
	v_bcnt_u32_b32 v206, vcc_hi, v206
	v_cmp_ge_u32_e32 vcc, v86, v3
	s_and_saveexec_b64 s[6:7], vcc
	s_cbranch_execz .LBB0_3925
	v_mbcnt_lo_u32_b32 v135, vcc_lo, v206
	v_mbcnt_hi_u32_b32 v135, vcc_hi, v135
	v_lshl_add_u32 v136, v135, 2, s58
	ds_write_b32 v136, v86
	v_add_u16_e32 v136, 0x1440, v134
	v_lshl_add_u32 v135, v135, 1, s92
	ds_write_b16 v135, v136
.LBB0_3925:
	s_or_b64 exec, exec, s[6:7]
	v_bcnt_u32_b32 v206, vcc_lo, v206
	v_bcnt_u32_b32 v206, vcc_hi, v206
	v_cmp_ge_u32_e32 vcc, v89, v3
	s_and_saveexec_b64 s[6:7], vcc
	s_cbranch_execz .LBB0_3927
	v_mbcnt_lo_u32_b32 v135, vcc_lo, v206
	v_mbcnt_hi_u32_b32 v135, vcc_hi, v135
	v_lshl_add_u32 v136, v135, 2, s58
	ds_write_b32 v136, v89
	v_add_u16_e32 v136, 0x1480, v134
	v_lshl_add_u32 v135, v135, 1, s92
	ds_write_b16 v135, v136
.LBB0_3927:
	s_or_b64 exec, exec, s[6:7]
	v_bcnt_u32_b32 v206, vcc_lo, v206
	v_bcnt_u32_b32 v206, vcc_hi, v206
	v_cmp_ge_u32_e32 vcc, v88, v3
	s_and_saveexec_b64 s[6:7], vcc
	s_cbranch_execz .LBB0_3929
	v_mbcnt_lo_u32_b32 v135, vcc_lo, v206
	v_mbcnt_hi_u32_b32 v135, vcc_hi, v135
	v_lshl_add_u32 v136, v135, 2, s58
	ds_write_b32 v136, v88
	v_add_u16_e32 v136, 0x14c0, v134
	v_lshl_add_u32 v135, v135, 1, s92
	ds_write_b16 v135, v136
.LBB0_3929:
	s_or_b64 exec, exec, s[6:7]
	v_bcnt_u32_b32 v206, vcc_lo, v206
	v_bcnt_u32_b32 v206, vcc_hi, v206
	v_cmp_ge_u32_e32 vcc, v91, v3
	s_and_saveexec_b64 s[6:7], vcc
	s_cbranch_execz .LBB0_3931
	v_mbcnt_lo_u32_b32 v135, vcc_lo, v206
	v_mbcnt_hi_u32_b32 v135, vcc_hi, v135
	v_lshl_add_u32 v136, v135, 2, s58
	ds_write_b32 v136, v91
	v_add_u16_e32 v136, 0x1500, v134
	v_lshl_add_u32 v135, v135, 1, s92
	ds_write_b16 v135, v136
.LBB0_3931:
	s_or_b64 exec, exec, s[6:7]
	v_bcnt_u32_b32 v206, vcc_lo, v206
	v_bcnt_u32_b32 v206, vcc_hi, v206
	v_cmp_ge_u32_e32 vcc, v90, v3
	s_and_saveexec_b64 s[6:7], vcc
	s_cbranch_execz .LBB0_3933
	v_mbcnt_lo_u32_b32 v135, vcc_lo, v206
	v_mbcnt_hi_u32_b32 v135, vcc_hi, v135
	v_lshl_add_u32 v136, v135, 2, s58
	ds_write_b32 v136, v90
	v_add_u16_e32 v136, 0x1540, v134
	v_lshl_add_u32 v135, v135, 1, s92
	ds_write_b16 v135, v136
.LBB0_3933:
	s_or_b64 exec, exec, s[6:7]
	v_bcnt_u32_b32 v206, vcc_lo, v206
	v_bcnt_u32_b32 v206, vcc_hi, v206
	v_cmp_ge_u32_e32 vcc, v93, v3
	s_and_saveexec_b64 s[6:7], vcc
	s_cbranch_execz .LBB0_3935
	v_mbcnt_lo_u32_b32 v135, vcc_lo, v206
	v_mbcnt_hi_u32_b32 v135, vcc_hi, v135
	v_lshl_add_u32 v136, v135, 2, s58
	ds_write_b32 v136, v93
	v_add_u16_e32 v136, 0x1580, v134
	v_lshl_add_u32 v135, v135, 1, s92
	ds_write_b16 v135, v136
.LBB0_3935:
	s_or_b64 exec, exec, s[6:7]
	v_bcnt_u32_b32 v206, vcc_lo, v206
	v_bcnt_u32_b32 v206, vcc_hi, v206
	v_cmp_ge_u32_e32 vcc, v92, v3
	s_and_saveexec_b64 s[6:7], vcc
	s_cbranch_execz .LBB0_3937
	v_mbcnt_lo_u32_b32 v135, vcc_lo, v206
	v_mbcnt_hi_u32_b32 v135, vcc_hi, v135
	v_lshl_add_u32 v136, v135, 2, s58
	ds_write_b32 v136, v92
	v_add_u16_e32 v136, 0x15c0, v134
	v_lshl_add_u32 v135, v135, 1, s92
	ds_write_b16 v135, v136
.LBB0_3937:
	s_or_b64 exec, exec, s[6:7]
	v_bcnt_u32_b32 v206, vcc_lo, v206
	v_bcnt_u32_b32 v206, vcc_hi, v206
	v_cmp_ge_u32_e32 vcc, v95, v3
	s_and_saveexec_b64 s[6:7], vcc
	s_cbranch_execz .LBB0_3939
	v_mbcnt_lo_u32_b32 v135, vcc_lo, v206
	v_mbcnt_hi_u32_b32 v135, vcc_hi, v135
	v_lshl_add_u32 v136, v135, 2, s58
	ds_write_b32 v136, v95
	v_add_u16_e32 v136, 0x1600, v134
	v_lshl_add_u32 v135, v135, 1, s92
	ds_write_b16 v135, v136
.LBB0_3939:
	s_or_b64 exec, exec, s[6:7]
	v_bcnt_u32_b32 v206, vcc_lo, v206
	v_bcnt_u32_b32 v206, vcc_hi, v206
	v_cmp_ge_u32_e32 vcc, v94, v3
	s_and_saveexec_b64 s[6:7], vcc
	s_cbranch_execz .LBB0_3941
	v_mbcnt_lo_u32_b32 v135, vcc_lo, v206
	v_mbcnt_hi_u32_b32 v135, vcc_hi, v135
	v_lshl_add_u32 v136, v135, 2, s58
	ds_write_b32 v136, v94
	v_add_u16_e32 v136, 0x1640, v134
	v_lshl_add_u32 v135, v135, 1, s92
	ds_write_b16 v135, v136
.LBB0_3941:
	s_or_b64 exec, exec, s[6:7]
	v_bcnt_u32_b32 v206, vcc_lo, v206
	v_bcnt_u32_b32 v206, vcc_hi, v206
	v_cmp_ge_u32_e32 vcc, v97, v3
	s_and_saveexec_b64 s[6:7], vcc
	s_cbranch_execz .LBB0_3943
	v_mbcnt_lo_u32_b32 v135, vcc_lo, v206
	v_mbcnt_hi_u32_b32 v135, vcc_hi, v135
	v_lshl_add_u32 v136, v135, 2, s58
	ds_write_b32 v136, v97
	v_add_u16_e32 v136, 0x1680, v134
	v_lshl_add_u32 v135, v135, 1, s92
	ds_write_b16 v135, v136
.LBB0_3943:
	s_or_b64 exec, exec, s[6:7]
	v_bcnt_u32_b32 v206, vcc_lo, v206
	v_bcnt_u32_b32 v206, vcc_hi, v206
	v_cmp_ge_u32_e32 vcc, v96, v3
	s_and_saveexec_b64 s[6:7], vcc
	s_cbranch_execz .LBB0_3945
	v_mbcnt_lo_u32_b32 v135, vcc_lo, v206
	v_mbcnt_hi_u32_b32 v135, vcc_hi, v135
	v_lshl_add_u32 v136, v135, 2, s58
	ds_write_b32 v136, v96
	v_add_u16_e32 v136, 0x16c0, v134
	v_lshl_add_u32 v135, v135, 1, s92
	ds_write_b16 v135, v136
.LBB0_3945:
	s_or_b64 exec, exec, s[6:7]
	v_bcnt_u32_b32 v206, vcc_lo, v206
	v_bcnt_u32_b32 v206, vcc_hi, v206
	v_cmp_ge_u32_e32 vcc, v99, v3
	s_and_saveexec_b64 s[6:7], vcc
	s_cbranch_execz .LBB0_3947
	v_mbcnt_lo_u32_b32 v135, vcc_lo, v206
	v_mbcnt_hi_u32_b32 v135, vcc_hi, v135
	v_lshl_add_u32 v136, v135, 2, s58
	ds_write_b32 v136, v99
	v_add_u16_e32 v136, 0x1700, v134
	v_lshl_add_u32 v135, v135, 1, s92
	ds_write_b16 v135, v136
.LBB0_3947:
	s_or_b64 exec, exec, s[6:7]
	v_bcnt_u32_b32 v206, vcc_lo, v206
	v_bcnt_u32_b32 v206, vcc_hi, v206
	v_cmp_ge_u32_e32 vcc, v98, v3
	s_and_saveexec_b64 s[6:7], vcc
	s_cbranch_execz .LBB0_3949
	v_mbcnt_lo_u32_b32 v135, vcc_lo, v206
	v_mbcnt_hi_u32_b32 v135, vcc_hi, v135
	v_lshl_add_u32 v136, v135, 2, s58
	ds_write_b32 v136, v98
	v_add_u16_e32 v136, 0x1740, v134
	v_lshl_add_u32 v135, v135, 1, s92
	ds_write_b16 v135, v136
.LBB0_3949:
	s_or_b64 exec, exec, s[6:7]
	v_bcnt_u32_b32 v206, vcc_lo, v206
	v_bcnt_u32_b32 v206, vcc_hi, v206
	v_cmp_ge_u32_e32 vcc, v101, v3
	s_and_saveexec_b64 s[6:7], vcc
	s_cbranch_execz .LBB0_3951
	v_mbcnt_lo_u32_b32 v135, vcc_lo, v206
	v_mbcnt_hi_u32_b32 v135, vcc_hi, v135
	v_lshl_add_u32 v136, v135, 2, s58
	ds_write_b32 v136, v101
	v_add_u16_e32 v136, 0x1780, v134
	v_lshl_add_u32 v135, v135, 1, s92
	ds_write_b16 v135, v136
.LBB0_3951:
	s_or_b64 exec, exec, s[6:7]
	v_bcnt_u32_b32 v206, vcc_lo, v206
	v_bcnt_u32_b32 v206, vcc_hi, v206
	v_cmp_ge_u32_e32 vcc, v100, v3
	s_and_saveexec_b64 s[6:7], vcc
	s_cbranch_execz .LBB0_3953
	v_mbcnt_lo_u32_b32 v135, vcc_lo, v206
	v_mbcnt_hi_u32_b32 v135, vcc_hi, v135
	v_lshl_add_u32 v136, v135, 2, s58
	v_add_u16_e32 v134, 0x17c0, v134
	v_lshl_add_u32 v135, v135, 1, s92
	ds_write_b32 v136, v100
	ds_write_b16 v135, v134

.LBB0_3956:
	v_mov_b32_e32 v134, v30
	v_cmp_ge_u32_e32 vcc, v39, v3
	s_and_saveexec_b64 s[6:7], vcc
	s_cbranch_execz .LBB0_3958
	v_mbcnt_lo_u32_b32 v135, vcc_lo, v206
	v_mbcnt_hi_u32_b32 v135, vcc_hi, v135
	v_lshl_add_u32 v136, v135, 2, s58
	ds_write_b32 v136, v39
	v_add_u16_e32 v136, 0x800, v134
	v_lshl_add_u32 v135, v135, 1, s92
	ds_write_b16 v135, v136
.LBB0_3958:
	s_or_b64 exec, exec, s[6:7]
	v_bcnt_u32_b32 v206, vcc_lo, v206
	v_bcnt_u32_b32 v206, vcc_hi, v206
	v_cmp_ge_u32_e32 vcc, v38, v3
	s_and_saveexec_b64 s[6:7], vcc
	s_cbranch_execz .LBB0_3960
	v_mbcnt_lo_u32_b32 v135, vcc_lo, v206
	v_mbcnt_hi_u32_b32 v135, vcc_hi, v135
	v_lshl_add_u32 v136, v135, 2, s58
	ds_write_b32 v136, v38
	v_add_u16_e32 v136, 0x840, v134
	v_lshl_add_u32 v135, v135, 1, s92
	ds_write_b16 v135, v136
.LBB0_3960:
	s_or_b64 exec, exec, s[6:7]
	v_bcnt_u32_b32 v206, vcc_lo, v206
	v_bcnt_u32_b32 v206, vcc_hi, v206
	v_cmp_ge_u32_e32 vcc, v41, v3
	s_and_saveexec_b64 s[6:7], vcc
	s_cbranch_execz .LBB0_3962
	v_mbcnt_lo_u32_b32 v135, vcc_lo, v206
	v_mbcnt_hi_u32_b32 v135, vcc_hi, v135
	v_lshl_add_u32 v136, v135, 2, s58
	ds_write_b32 v136, v41
	v_add_u16_e32 v136, 0x880, v134
	v_lshl_add_u32 v135, v135, 1, s92
	ds_write_b16 v135, v136
.LBB0_3962:
	s_or_b64 exec, exec, s[6:7]
	v_bcnt_u32_b32 v206, vcc_lo, v206
	v_bcnt_u32_b32 v206, vcc_hi, v206
	v_cmp_ge_u32_e32 vcc, v40, v3
	s_and_saveexec_b64 s[6:7], vcc
	s_cbranch_execz .LBB0_3964
	v_mbcnt_lo_u32_b32 v135, vcc_lo, v206
	v_mbcnt_hi_u32_b32 v135, vcc_hi, v135
	v_lshl_add_u32 v136, v135, 2, s58
	ds_write_b32 v136, v40
	v_add_u16_e32 v136, 0x8c0, v134
	v_lshl_add_u32 v135, v135, 1, s92
	ds_write_b16 v135, v136
.LBB0_3964:
	s_or_b64 exec, exec, s[6:7]
	v_bcnt_u32_b32 v206, vcc_lo, v206
	v_bcnt_u32_b32 v206, vcc_hi, v206
	v_cmp_ge_u32_e32 vcc, v43, v3
	s_and_saveexec_b64 s[6:7], vcc
	s_cbranch_execz .LBB0_3966
	v_mbcnt_lo_u32_b32 v135, vcc_lo, v206
	v_mbcnt_hi_u32_b32 v135, vcc_hi, v135
	v_lshl_add_u32 v136, v135, 2, s58
	ds_write_b32 v136, v43
	v_add_u16_e32 v136, 0x900, v134
	v_lshl_add_u32 v135, v135, 1, s92
	ds_write_b16 v135, v136
.LBB0_3966:
	s_or_b64 exec, exec, s[6:7]
	v_bcnt_u32_b32 v206, vcc_lo, v206
	v_bcnt_u32_b32 v206, vcc_hi, v206
	v_cmp_ge_u32_e32 vcc, v42, v3
	s_and_saveexec_b64 s[6:7], vcc
	s_cbranch_execz .LBB0_3968
	v_mbcnt_lo_u32_b32 v135, vcc_lo, v206
	v_mbcnt_hi_u32_b32 v135, vcc_hi, v135
	v_lshl_add_u32 v136, v135, 2, s58
	ds_write_b32 v136, v42
	v_add_u16_e32 v136, 0x940, v134
	v_lshl_add_u32 v135, v135, 1, s92
	ds_write_b16 v135, v136
.LBB0_3968:
	s_or_b64 exec, exec, s[6:7]
	v_bcnt_u32_b32 v206, vcc_lo, v206
	v_bcnt_u32_b32 v206, vcc_hi, v206
	v_cmp_ge_u32_e32 vcc, v45, v3
	s_and_saveexec_b64 s[6:7], vcc
	s_cbranch_execz .LBB0_3970
	v_mbcnt_lo_u32_b32 v135, vcc_lo, v206
	v_mbcnt_hi_u32_b32 v135, vcc_hi, v135
	v_lshl_add_u32 v136, v135, 2, s58
	ds_write_b32 v136, v45
	v_add_u16_e32 v136, 0x980, v134
	v_lshl_add_u32 v135, v135, 1, s92
	ds_write_b16 v135, v136
.LBB0_3970:
	s_or_b64 exec, exec, s[6:7]
	v_bcnt_u32_b32 v206, vcc_lo, v206
	v_bcnt_u32_b32 v206, vcc_hi, v206
	v_cmp_ge_u32_e32 vcc, v44, v3
	s_and_saveexec_b64 s[6:7], vcc
	s_cbranch_execz .LBB0_3972
	v_mbcnt_lo_u32_b32 v135, vcc_lo, v206
	v_mbcnt_hi_u32_b32 v135, vcc_hi, v135
	v_lshl_add_u32 v136, v135, 2, s58
	ds_write_b32 v136, v44
	v_add_u16_e32 v136, 0x9c0, v134
	v_lshl_add_u32 v135, v135, 1, s92
	ds_write_b16 v135, v136
.LBB0_3972:
	s_or_b64 exec, exec, s[6:7]
	v_bcnt_u32_b32 v206, vcc_lo, v206
	v_bcnt_u32_b32 v206, vcc_hi, v206
	v_cmp_ge_u32_e32 vcc, v47, v3
	s_and_saveexec_b64 s[6:7], vcc
	s_cbranch_execz .LBB0_3974
	v_mbcnt_lo_u32_b32 v135, vcc_lo, v206
	v_mbcnt_hi_u32_b32 v135, vcc_hi, v135
	v_lshl_add_u32 v136, v135, 2, s58
	ds_write_b32 v136, v47
	v_add_u16_e32 v136, 0xa00, v134
	v_lshl_add_u32 v135, v135, 1, s92
	ds_write_b16 v135, v136
.LBB0_3974:
	s_or_b64 exec, exec, s[6:7]
	v_bcnt_u32_b32 v206, vcc_lo, v206
	v_bcnt_u32_b32 v206, vcc_hi, v206
	v_cmp_ge_u32_e32 vcc, v46, v3
	s_and_saveexec_b64 s[6:7], vcc
	s_cbranch_execz .LBB0_3976
	v_mbcnt_lo_u32_b32 v135, vcc_lo, v206
	v_mbcnt_hi_u32_b32 v135, vcc_hi, v135
	v_lshl_add_u32 v136, v135, 2, s58
	ds_write_b32 v136, v46
	v_add_u16_e32 v136, 0xa40, v134
	v_lshl_add_u32 v135, v135, 1, s92
	ds_write_b16 v135, v136
.LBB0_3976:
	s_or_b64 exec, exec, s[6:7]
	v_bcnt_u32_b32 v206, vcc_lo, v206
	v_bcnt_u32_b32 v206, vcc_hi, v206
	v_cmp_ge_u32_e32 vcc, v49, v3
	s_and_saveexec_b64 s[6:7], vcc
	s_cbranch_execz .LBB0_3978
	v_mbcnt_lo_u32_b32 v135, vcc_lo, v206
	v_mbcnt_hi_u32_b32 v135, vcc_hi, v135
	v_lshl_add_u32 v136, v135, 2, s58
	ds_write_b32 v136, v49
	v_add_u16_e32 v136, 0xa80, v134
	v_lshl_add_u32 v135, v135, 1, s92
	ds_write_b16 v135, v136
.LBB0_3978:
	s_or_b64 exec, exec, s[6:7]
	v_bcnt_u32_b32 v206, vcc_lo, v206
	v_bcnt_u32_b32 v206, vcc_hi, v206
	v_cmp_ge_u32_e32 vcc, v48, v3
	s_and_saveexec_b64 s[6:7], vcc
	s_cbranch_execz .LBB0_3980
	v_mbcnt_lo_u32_b32 v135, vcc_lo, v206
	v_mbcnt_hi_u32_b32 v135, vcc_hi, v135
	v_lshl_add_u32 v136, v135, 2, s58
	ds_write_b32 v136, v48
	v_add_u16_e32 v136, 0xac0, v134
	v_lshl_add_u32 v135, v135, 1, s92
	ds_write_b16 v135, v136
.LBB0_3980:
	s_or_b64 exec, exec, s[6:7]
	v_bcnt_u32_b32 v206, vcc_lo, v206
	v_bcnt_u32_b32 v206, vcc_hi, v206
	v_cmp_ge_u32_e32 vcc, v51, v3
	s_and_saveexec_b64 s[6:7], vcc
	s_cbranch_execz .LBB0_3982
	v_mbcnt_lo_u32_b32 v135, vcc_lo, v206
	v_mbcnt_hi_u32_b32 v135, vcc_hi, v135
	v_lshl_add_u32 v136, v135, 2, s58
	ds_write_b32 v136, v51
	v_add_u16_e32 v136, 0xb00, v134
	v_lshl_add_u32 v135, v135, 1, s92
	ds_write_b16 v135, v136
.LBB0_3982:
	s_or_b64 exec, exec, s[6:7]
	v_bcnt_u32_b32 v206, vcc_lo, v206
	v_bcnt_u32_b32 v206, vcc_hi, v206
	v_cmp_ge_u32_e32 vcc, v50, v3
	s_and_saveexec_b64 s[6:7], vcc
	s_cbranch_execz .LBB0_3984
	v_mbcnt_lo_u32_b32 v135, vcc_lo, v206
	v_mbcnt_hi_u32_b32 v135, vcc_hi, v135
	v_lshl_add_u32 v136, v135, 2, s58
	ds_write_b32 v136, v50
	v_add_u16_e32 v136, 0xb40, v134
	v_lshl_add_u32 v135, v135, 1, s92
	ds_write_b16 v135, v136
.LBB0_3984:
	s_or_b64 exec, exec, s[6:7]
	v_bcnt_u32_b32 v206, vcc_lo, v206
	v_bcnt_u32_b32 v206, vcc_hi, v206
	v_cmp_ge_u32_e32 vcc, v53, v3
	s_and_saveexec_b64 s[6:7], vcc
	s_cbranch_execz .LBB0_3986
	v_mbcnt_lo_u32_b32 v135, vcc_lo, v206
	v_mbcnt_hi_u32_b32 v135, vcc_hi, v135
	v_lshl_add_u32 v136, v135, 2, s58
	ds_write_b32 v136, v53
	v_add_u16_e32 v136, 0xb80, v134
	v_lshl_add_u32 v135, v135, 1, s92
	ds_write_b16 v135, v136
.LBB0_3986:
	s_or_b64 exec, exec, s[6:7]
	v_bcnt_u32_b32 v206, vcc_lo, v206
	v_bcnt_u32_b32 v206, vcc_hi, v206
	v_cmp_ge_u32_e32 vcc, v52, v3
	s_and_saveexec_b64 s[6:7], vcc
	s_cbranch_execz .LBB0_3988
	v_mbcnt_lo_u32_b32 v135, vcc_lo, v206
	v_mbcnt_hi_u32_b32 v135, vcc_hi, v135
	v_lshl_add_u32 v136, v135, 2, s58
	v_add_u16_e32 v134, 0xbc0, v134
	v_lshl_add_u32 v135, v135, 1, s92
	ds_write_b32 v136, v52
	ds_write_b16 v135, v134
.LBB0_3988:
	s_or_b64 exec, exec, s[6:7]
	v_bcnt_u32_b32 v206, vcc_lo, v206
	v_bcnt_u32_b32 v206, vcc_hi, v206
	s_andn2_b64 vcc, exec, s[0:1]
	s_cbranch_vccz .LBB0_3887

.LBB0_3990:
	v_mov_b32_e32 v134, v30
	v_cmp_ge_u32_e32 vcc, v71, v3
	s_and_saveexec_b64 s[6:7], vcc
	s_cbranch_execz .LBB0_3992
	v_mbcnt_lo_u32_b32 v135, vcc_lo, v206
	v_mbcnt_hi_u32_b32 v135, vcc_hi, v135
	v_lshl_add_u32 v136, v135, 2, s58
	ds_write_b32 v136, v71
	v_add_u16_e32 v136, 0x1000, v134
	v_lshl_add_u32 v135, v135, 1, s92
	ds_write_b16 v135, v136
.LBB0_3992:
	s_or_b64 exec, exec, s[6:7]
	v_bcnt_u32_b32 v206, vcc_lo, v206
	v_bcnt_u32_b32 v206, vcc_hi, v206
	v_cmp_ge_u32_e32 vcc, v70, v3
	s_and_saveexec_b64 s[6:7], vcc
	s_cbranch_execz .LBB0_3994
	v_mbcnt_lo_u32_b32 v135, vcc_lo, v206
	v_mbcnt_hi_u32_b32 v135, vcc_hi, v135
	v_lshl_add_u32 v136, v135, 2, s58
	ds_write_b32 v136, v70
	v_add_u16_e32 v136, 0x1040, v134
	v_lshl_add_u32 v135, v135, 1, s92
	ds_write_b16 v135, v136
.LBB0_3994:
	s_or_b64 exec, exec, s[6:7]
	v_bcnt_u32_b32 v206, vcc_lo, v206
	v_bcnt_u32_b32 v206, vcc_hi, v206
	v_cmp_ge_u32_e32 vcc, v73, v3
	s_and_saveexec_b64 s[6:7], vcc
	s_cbranch_execz .LBB0_3996
	v_mbcnt_lo_u32_b32 v135, vcc_lo, v206
	v_mbcnt_hi_u32_b32 v135, vcc_hi, v135
	v_lshl_add_u32 v136, v135, 2, s58
	ds_write_b32 v136, v73
	v_add_u16_e32 v136, 0x1080, v134
	v_lshl_add_u32 v135, v135, 1, s92
	ds_write_b16 v135, v136
.LBB0_3996:
	s_or_b64 exec, exec, s[6:7]
	v_bcnt_u32_b32 v206, vcc_lo, v206
	v_bcnt_u32_b32 v206, vcc_hi, v206
	v_cmp_ge_u32_e32 vcc, v72, v3
	s_and_saveexec_b64 s[6:7], vcc
	s_cbranch_execz .LBB0_3998
	v_mbcnt_lo_u32_b32 v135, vcc_lo, v206
	v_mbcnt_hi_u32_b32 v135, vcc_hi, v135
	v_lshl_add_u32 v136, v135, 2, s58
	ds_write_b32 v136, v72
	v_add_u16_e32 v136, 0x10c0, v134
	v_lshl_add_u32 v135, v135, 1, s92
	ds_write_b16 v135, v136
.LBB0_3998:
	s_or_b64 exec, exec, s[6:7]
	v_bcnt_u32_b32 v206, vcc_lo, v206
	v_bcnt_u32_b32 v206, vcc_hi, v206
	v_cmp_ge_u32_e32 vcc, v75, v3
	s_and_saveexec_b64 s[6:7], vcc
	s_cbranch_execz .LBB0_4000
	v_mbcnt_lo_u32_b32 v135, vcc_lo, v206
	v_mbcnt_hi_u32_b32 v135, vcc_hi, v135
	v_lshl_add_u32 v136, v135, 2, s58
	ds_write_b32 v136, v75
	v_add_u16_e32 v136, 0x1100, v134
	v_lshl_add_u32 v135, v135, 1, s92
	ds_write_b16 v135, v136
.LBB0_4000:
	s_or_b64 exec, exec, s[6:7]
	v_bcnt_u32_b32 v206, vcc_lo, v206
	v_bcnt_u32_b32 v206, vcc_hi, v206
	v_cmp_ge_u32_e32 vcc, v74, v3
	s_and_saveexec_b64 s[6:7], vcc
	s_cbranch_execz .LBB0_4002
	v_mbcnt_lo_u32_b32 v135, vcc_lo, v206
	v_mbcnt_hi_u32_b32 v135, vcc_hi, v135
	v_lshl_add_u32 v136, v135, 2, s58
	ds_write_b32 v136, v74
	v_add_u16_e32 v136, 0x1140, v134
	v_lshl_add_u32 v135, v135, 1, s92
	ds_write_b16 v135, v136
.LBB0_4002:
	s_or_b64 exec, exec, s[6:7]
	v_bcnt_u32_b32 v206, vcc_lo, v206
	v_bcnt_u32_b32 v206, vcc_hi, v206
	v_cmp_ge_u32_e32 vcc, v77, v3
	s_and_saveexec_b64 s[6:7], vcc
	s_cbranch_execz .LBB0_4004
	v_mbcnt_lo_u32_b32 v135, vcc_lo, v206
	v_mbcnt_hi_u32_b32 v135, vcc_hi, v135
	v_lshl_add_u32 v136, v135, 2, s58
	ds_write_b32 v136, v77
	v_add_u16_e32 v136, 0x1180, v134
	v_lshl_add_u32 v135, v135, 1, s92
	ds_write_b16 v135, v136
.LBB0_4004:
	s_or_b64 exec, exec, s[6:7]
	v_bcnt_u32_b32 v206, vcc_lo, v206
	v_bcnt_u32_b32 v206, vcc_hi, v206
	v_cmp_ge_u32_e32 vcc, v76, v3
	s_and_saveexec_b64 s[6:7], vcc
	s_cbranch_execz .LBB0_4006
	v_mbcnt_lo_u32_b32 v135, vcc_lo, v206
	v_mbcnt_hi_u32_b32 v135, vcc_hi, v135
	v_lshl_add_u32 v136, v135, 2, s58
	ds_write_b32 v136, v76
	v_add_u16_e32 v136, 0x11c0, v134
	v_lshl_add_u32 v135, v135, 1, s92
	ds_write_b16 v135, v136
.LBB0_4006:
	s_or_b64 exec, exec, s[6:7]
	v_bcnt_u32_b32 v206, vcc_lo, v206
	v_bcnt_u32_b32 v206, vcc_hi, v206
	v_cmp_ge_u32_e32 vcc, v79, v3
	s_and_saveexec_b64 s[6:7], vcc
	s_cbranch_execz .LBB0_4008
	v_mbcnt_lo_u32_b32 v135, vcc_lo, v206
	v_mbcnt_hi_u32_b32 v135, vcc_hi, v135
	v_lshl_add_u32 v136, v135, 2, s58
	ds_write_b32 v136, v79
	v_add_u16_e32 v136, 0x1200, v134
	v_lshl_add_u32 v135, v135, 1, s92
	ds_write_b16 v135, v136
.LBB0_4008:
	s_or_b64 exec, exec, s[6:7]
	v_bcnt_u32_b32 v206, vcc_lo, v206
	v_bcnt_u32_b32 v206, vcc_hi, v206
	v_cmp_ge_u32_e32 vcc, v78, v3
	s_and_saveexec_b64 s[6:7], vcc
	s_cbranch_execz .LBB0_4010
	v_mbcnt_lo_u32_b32 v135, vcc_lo, v206
	v_mbcnt_hi_u32_b32 v135, vcc_hi, v135
	v_lshl_add_u32 v136, v135, 2, s58
	ds_write_b32 v136, v78
	v_add_u16_e32 v136, 0x1240, v134
	v_lshl_add_u32 v135, v135, 1, s92
	ds_write_b16 v135, v136
.LBB0_4010:
	s_or_b64 exec, exec, s[6:7]
	v_bcnt_u32_b32 v206, vcc_lo, v206
	v_bcnt_u32_b32 v206, vcc_hi, v206
	v_cmp_ge_u32_e32 vcc, v81, v3
	s_and_saveexec_b64 s[6:7], vcc
	s_cbranch_execz .LBB0_4012
	v_mbcnt_lo_u32_b32 v135, vcc_lo, v206
	v_mbcnt_hi_u32_b32 v135, vcc_hi, v135
	v_lshl_add_u32 v136, v135, 2, s58
	ds_write_b32 v136, v81
	v_add_u16_e32 v136, 0x1280, v134
	v_lshl_add_u32 v135, v135, 1, s92
	ds_write_b16 v135, v136
.LBB0_4012:
	s_or_b64 exec, exec, s[6:7]
	v_bcnt_u32_b32 v206, vcc_lo, v206
	v_bcnt_u32_b32 v206, vcc_hi, v206
	v_cmp_ge_u32_e32 vcc, v80, v3
	s_and_saveexec_b64 s[6:7], vcc
	s_cbranch_execz .LBB0_4014
	v_mbcnt_lo_u32_b32 v135, vcc_lo, v206
	v_mbcnt_hi_u32_b32 v135, vcc_hi, v135
	v_lshl_add_u32 v136, v135, 2, s58
	ds_write_b32 v136, v80
	v_add_u16_e32 v136, 0x12c0, v134
	v_lshl_add_u32 v135, v135, 1, s92
	ds_write_b16 v135, v136
.LBB0_4014:
	s_or_b64 exec, exec, s[6:7]
	v_bcnt_u32_b32 v206, vcc_lo, v206
	v_bcnt_u32_b32 v206, vcc_hi, v206
	v_cmp_ge_u32_e32 vcc, v83, v3
	s_and_saveexec_b64 s[6:7], vcc
	s_cbranch_execz .LBB0_4016
	v_mbcnt_lo_u32_b32 v135, vcc_lo, v206
	v_mbcnt_hi_u32_b32 v135, vcc_hi, v135
	v_lshl_add_u32 v136, v135, 2, s58
	ds_write_b32 v136, v83
	v_add_u16_e32 v136, 0x1300, v134
	v_lshl_add_u32 v135, v135, 1, s92
	ds_write_b16 v135, v136
.LBB0_4016:
	s_or_b64 exec, exec, s[6:7]
	v_bcnt_u32_b32 v206, vcc_lo, v206
	v_bcnt_u32_b32 v206, vcc_hi, v206
	v_cmp_ge_u32_e32 vcc, v82, v3
	s_and_saveexec_b64 s[6:7], vcc
	s_cbranch_execz .LBB0_4018
	v_mbcnt_lo_u32_b32 v135, vcc_lo, v206
	v_mbcnt_hi_u32_b32 v135, vcc_hi, v135
	v_lshl_add_u32 v136, v135, 2, s58
	ds_write_b32 v136, v82
	v_add_u16_e32 v136, 0x1340, v134
	v_lshl_add_u32 v135, v135, 1, s92
	ds_write_b16 v135, v136
.LBB0_4018:
	s_or_b64 exec, exec, s[6:7]
	v_bcnt_u32_b32 v206, vcc_lo, v206
	v_bcnt_u32_b32 v206, vcc_hi, v206
	v_cmp_ge_u32_e32 vcc, v85, v3
	s_and_saveexec_b64 s[6:7], vcc
	s_cbranch_execz .LBB0_4020
	v_mbcnt_lo_u32_b32 v135, vcc_lo, v206
	v_mbcnt_hi_u32_b32 v135, vcc_hi, v135
	v_lshl_add_u32 v136, v135, 2, s58
	ds_write_b32 v136, v85
	v_add_u16_e32 v136, 0x1380, v134
	v_lshl_add_u32 v135, v135, 1, s92
	ds_write_b16 v135, v136
.LBB0_4020:
	s_or_b64 exec, exec, s[6:7]
	v_bcnt_u32_b32 v206, vcc_lo, v206
	v_bcnt_u32_b32 v206, vcc_hi, v206
	v_cmp_ge_u32_e32 vcc, v84, v3
	s_and_saveexec_b64 s[6:7], vcc
	s_cbranch_execz .LBB0_4022
	v_mbcnt_lo_u32_b32 v135, vcc_lo, v206
	v_mbcnt_hi_u32_b32 v135, vcc_hi, v135
	v_lshl_add_u32 v136, v135, 2, s58
	v_add_u16_e32 v134, 0x13c0, v134
	v_lshl_add_u32 v135, v135, 1, s92
	ds_write_b32 v136, v84
	ds_write_b16 v135, v134
.LBB0_4022:
	s_or_b64 exec, exec, s[6:7]
	v_bcnt_u32_b32 v206, vcc_lo, v206
	v_bcnt_u32_b32 v206, vcc_hi, v206
	s_andn2_b64 vcc, exec, s[94:95]
	s_cbranch_vccz .LBB0_3921

.LBB0_4024:
	v_mov_b32_e32 v134, v30
	v_cmp_ge_u32_e32 vcc, v103, v3
	s_and_saveexec_b64 s[6:7], vcc
	s_cbranch_execz .LBB0_4026
	v_mbcnt_lo_u32_b32 v135, vcc_lo, v206
	v_mbcnt_hi_u32_b32 v135, vcc_hi, v135
	v_lshl_add_u32 v136, v135, 2, s58
	ds_write_b32 v136, v103
	v_add_u16_e32 v136, 0x1800, v134
	v_lshl_add_u32 v135, v135, 1, s92
	ds_write_b16 v135, v136
.LBB0_4026:
	s_or_b64 exec, exec, s[6:7]
	v_bcnt_u32_b32 v206, vcc_lo, v206
	v_bcnt_u32_b32 v206, vcc_hi, v206
	v_cmp_ge_u32_e32 vcc, v102, v3
	s_and_saveexec_b64 s[6:7], vcc
	s_cbranch_execz .LBB0_4028
	v_mbcnt_lo_u32_b32 v135, vcc_lo, v206
	v_mbcnt_hi_u32_b32 v135, vcc_hi, v135
	v_lshl_add_u32 v136, v135, 2, s58
	ds_write_b32 v136, v102
	v_add_u16_e32 v136, 0x1840, v134
	v_lshl_add_u32 v135, v135, 1, s92
	ds_write_b16 v135, v136
.LBB0_4028:
	s_or_b64 exec, exec, s[6:7]
	v_bcnt_u32_b32 v206, vcc_lo, v206
	v_bcnt_u32_b32 v206, vcc_hi, v206
	v_cmp_ge_u32_e32 vcc, v105, v3
	s_and_saveexec_b64 s[6:7], vcc
	s_cbranch_execz .LBB0_4030
	v_mbcnt_lo_u32_b32 v135, vcc_lo, v206
	v_mbcnt_hi_u32_b32 v135, vcc_hi, v135
	v_lshl_add_u32 v136, v135, 2, s58
	ds_write_b32 v136, v105
	v_add_u16_e32 v136, 0x1880, v134
	v_lshl_add_u32 v135, v135, 1, s92
	ds_write_b16 v135, v136
.LBB0_4030:
	s_or_b64 exec, exec, s[6:7]
	v_bcnt_u32_b32 v206, vcc_lo, v206
	v_bcnt_u32_b32 v206, vcc_hi, v206
	v_cmp_ge_u32_e32 vcc, v104, v3
	s_and_saveexec_b64 s[6:7], vcc
	s_cbranch_execz .LBB0_4032
	v_mbcnt_lo_u32_b32 v135, vcc_lo, v206
	v_mbcnt_hi_u32_b32 v135, vcc_hi, v135
	v_lshl_add_u32 v136, v135, 2, s58
	ds_write_b32 v136, v104
	v_add_u16_e32 v136, 0x18c0, v134
	v_lshl_add_u32 v135, v135, 1, s92
	ds_write_b16 v135, v136
.LBB0_4032:
	s_or_b64 exec, exec, s[6:7]
	v_bcnt_u32_b32 v206, vcc_lo, v206
	v_bcnt_u32_b32 v206, vcc_hi, v206
	v_cmp_ge_u32_e32 vcc, v107, v3
	s_and_saveexec_b64 s[6:7], vcc
	s_cbranch_execz .LBB0_4034
	v_mbcnt_lo_u32_b32 v135, vcc_lo, v206
	v_mbcnt_hi_u32_b32 v135, vcc_hi, v135
	v_lshl_add_u32 v136, v135, 2, s58
	ds_write_b32 v136, v107
	v_add_u16_e32 v136, 0x1900, v134
	v_lshl_add_u32 v135, v135, 1, s92
	ds_write_b16 v135, v136
.LBB0_4034:
	s_or_b64 exec, exec, s[6:7]
	v_bcnt_u32_b32 v206, vcc_lo, v206
	v_bcnt_u32_b32 v206, vcc_hi, v206
	v_cmp_ge_u32_e32 vcc, v106, v3
	s_and_saveexec_b64 s[6:7], vcc
	s_cbranch_execz .LBB0_4036
	v_mbcnt_lo_u32_b32 v135, vcc_lo, v206
	v_mbcnt_hi_u32_b32 v135, vcc_hi, v135
	v_lshl_add_u32 v136, v135, 2, s58
	ds_write_b32 v136, v106
	v_add_u16_e32 v136, 0x1940, v134
	v_lshl_add_u32 v135, v135, 1, s92
	ds_write_b16 v135, v136
.LBB0_4036:
	s_or_b64 exec, exec, s[6:7]
	v_bcnt_u32_b32 v206, vcc_lo, v206
	v_bcnt_u32_b32 v206, vcc_hi, v206
	v_cmp_ge_u32_e32 vcc, v109, v3
	s_and_saveexec_b64 s[6:7], vcc
	s_cbranch_execz .LBB0_4038
	v_mbcnt_lo_u32_b32 v135, vcc_lo, v206
	v_mbcnt_hi_u32_b32 v135, vcc_hi, v135
	v_lshl_add_u32 v136, v135, 2, s58
	ds_write_b32 v136, v109
	v_add_u16_e32 v136, 0x1980, v134
	v_lshl_add_u32 v135, v135, 1, s92
	ds_write_b16 v135, v136
.LBB0_4038:
	s_or_b64 exec, exec, s[6:7]
	v_bcnt_u32_b32 v206, vcc_lo, v206
	v_bcnt_u32_b32 v206, vcc_hi, v206
	v_cmp_ge_u32_e32 vcc, v108, v3
	s_and_saveexec_b64 s[6:7], vcc
	s_cbranch_execz .LBB0_4040
	v_mbcnt_lo_u32_b32 v135, vcc_lo, v206
	v_mbcnt_hi_u32_b32 v135, vcc_hi, v135
	v_lshl_add_u32 v136, v135, 2, s58
	ds_write_b32 v136, v108
	v_add_u16_e32 v136, 0x19c0, v134
	v_lshl_add_u32 v135, v135, 1, s92
	ds_write_b16 v135, v136
.LBB0_4040:
	s_or_b64 exec, exec, s[6:7]
	v_bcnt_u32_b32 v206, vcc_lo, v206
	v_bcnt_u32_b32 v206, vcc_hi, v206
	v_cmp_ge_u32_e32 vcc, v111, v3
	s_and_saveexec_b64 s[6:7], vcc
	s_cbranch_execz .LBB0_4042
	v_mbcnt_lo_u32_b32 v135, vcc_lo, v206
	v_mbcnt_hi_u32_b32 v135, vcc_hi, v135
	v_lshl_add_u32 v136, v135, 2, s58
	ds_write_b32 v136, v111
	v_add_u16_e32 v136, 0x1a00, v134
	v_lshl_add_u32 v135, v135, 1, s92
	ds_write_b16 v135, v136
.LBB0_4042:
	s_or_b64 exec, exec, s[6:7]
	v_bcnt_u32_b32 v206, vcc_lo, v206
	v_bcnt_u32_b32 v206, vcc_hi, v206
	v_cmp_ge_u32_e32 vcc, v110, v3
	s_and_saveexec_b64 s[6:7], vcc
	s_cbranch_execz .LBB0_4044
	v_mbcnt_lo_u32_b32 v135, vcc_lo, v206
	v_mbcnt_hi_u32_b32 v135, vcc_hi, v135
	v_lshl_add_u32 v136, v135, 2, s58
	ds_write_b32 v136, v110
	v_add_u16_e32 v136, 0x1a40, v134
	v_lshl_add_u32 v135, v135, 1, s92
	ds_write_b16 v135, v136
.LBB0_4044:
	s_or_b64 exec, exec, s[6:7]
	v_bcnt_u32_b32 v206, vcc_lo, v206
	v_bcnt_u32_b32 v206, vcc_hi, v206
	v_cmp_ge_u32_e32 vcc, v113, v3
	s_and_saveexec_b64 s[6:7], vcc
	s_cbranch_execz .LBB0_4046
	v_mbcnt_lo_u32_b32 v135, vcc_lo, v206
	v_mbcnt_hi_u32_b32 v135, vcc_hi, v135
	v_lshl_add_u32 v136, v135, 2, s58
	ds_write_b32 v136, v113
	v_add_u16_e32 v136, 0x1a80, v134
	v_lshl_add_u32 v135, v135, 1, s92
	ds_write_b16 v135, v136
.LBB0_4046:
	s_or_b64 exec, exec, s[6:7]
	v_bcnt_u32_b32 v206, vcc_lo, v206
	v_bcnt_u32_b32 v206, vcc_hi, v206
	v_cmp_ge_u32_e32 vcc, v112, v3
	s_and_saveexec_b64 s[6:7], vcc
	s_cbranch_execz .LBB0_4048
	v_mbcnt_lo_u32_b32 v135, vcc_lo, v206
	v_mbcnt_hi_u32_b32 v135, vcc_hi, v135
	v_lshl_add_u32 v136, v135, 2, s58
	ds_write_b32 v136, v112
	v_add_u16_e32 v136, 0x1ac0, v134
	v_lshl_add_u32 v135, v135, 1, s92
	ds_write_b16 v135, v136
.LBB0_4048:
	s_or_b64 exec, exec, s[6:7]
	v_bcnt_u32_b32 v206, vcc_lo, v206
	v_bcnt_u32_b32 v206, vcc_hi, v206
	v_cmp_ge_u32_e32 vcc, v115, v3
	s_and_saveexec_b64 s[6:7], vcc
	s_cbranch_execz .LBB0_4050
	v_mbcnt_lo_u32_b32 v135, vcc_lo, v206
	v_mbcnt_hi_u32_b32 v135, vcc_hi, v135
	v_lshl_add_u32 v136, v135, 2, s58
	ds_write_b32 v136, v115
	v_add_u16_e32 v136, 0x1b00, v134
	v_lshl_add_u32 v135, v135, 1, s92
	ds_write_b16 v135, v136
.LBB0_4050:
	s_or_b64 exec, exec, s[6:7]
	v_bcnt_u32_b32 v206, vcc_lo, v206
	v_bcnt_u32_b32 v206, vcc_hi, v206
	v_cmp_ge_u32_e32 vcc, v114, v3
	s_and_saveexec_b64 s[6:7], vcc
	s_cbranch_execz .LBB0_4052
	v_mbcnt_lo_u32_b32 v135, vcc_lo, v206
	v_mbcnt_hi_u32_b32 v135, vcc_hi, v135
	v_lshl_add_u32 v136, v135, 2, s58
	ds_write_b32 v136, v114
	v_add_u16_e32 v136, 0x1b40, v134
	v_lshl_add_u32 v135, v135, 1, s92
	ds_write_b16 v135, v136
.LBB0_4052:
	s_or_b64 exec, exec, s[6:7]
	v_bcnt_u32_b32 v206, vcc_lo, v206
	v_bcnt_u32_b32 v206, vcc_hi, v206
	v_cmp_ge_u32_e32 vcc, v117, v3
	s_and_saveexec_b64 s[6:7], vcc
	s_cbranch_execz .LBB0_4054
	v_mbcnt_lo_u32_b32 v135, vcc_lo, v206
	v_mbcnt_hi_u32_b32 v135, vcc_hi, v135
	v_lshl_add_u32 v136, v135, 2, s58
	ds_write_b32 v136, v117
	v_add_u16_e32 v136, 0x1b80, v134
	v_lshl_add_u32 v135, v135, 1, s92
	ds_write_b16 v135, v136
.LBB0_4054:
	s_or_b64 exec, exec, s[6:7]
	v_bcnt_u32_b32 v206, vcc_lo, v206
	v_bcnt_u32_b32 v206, vcc_hi, v206
	v_cmp_ge_u32_e32 vcc, v116, v3
	s_and_saveexec_b64 s[6:7], vcc
	s_cbranch_execz .LBB0_4056
	v_mbcnt_lo_u32_b32 v135, vcc_lo, v206
	v_mbcnt_hi_u32_b32 v135, vcc_hi, v135
	v_lshl_add_u32 v136, v135, 2, s58
	v_add_u16_e32 v134, 0x1bc0, v134
	v_lshl_add_u32 v135, v135, 1, s92
	ds_write_b32 v136, v116
	ds_write_b16 v135, v134
.LBB0_4056:
	s_or_b64 exec, exec, s[6:7]
	v_bcnt_u32_b32 v206, vcc_lo, v206
	v_bcnt_u32_b32 v206, vcc_hi, v206
	s_andn2_b64 vcc, exec, s[64:65]
	s_cbranch_vccnz .LBB0_4090
.LBB0_4057:
	v_mov_b32_e32 v134, v30
	v_cmp_ge_u32_e32 vcc, v119, v3
	s_and_saveexec_b64 s[6:7], vcc
	s_cbranch_execz .LBB0_4059
	v_mbcnt_lo_u32_b32 v135, vcc_lo, v206
	v_mbcnt_hi_u32_b32 v135, vcc_hi, v135
	v_lshl_add_u32 v136, v135, 2, s58
	ds_write_b32 v136, v119
	v_add_u16_e32 v136, 0x1c00, v134
	v_lshl_add_u32 v135, v135, 1, s92
	ds_write_b16 v135, v136
.LBB0_4059:
	s_or_b64 exec, exec, s[6:7]
	v_bcnt_u32_b32 v206, vcc_lo, v206
	v_bcnt_u32_b32 v206, vcc_hi, v206
	v_cmp_ge_u32_e32 vcc, v118, v3
	s_and_saveexec_b64 s[6:7], vcc
	s_cbranch_execz .LBB0_4061
	v_mbcnt_lo_u32_b32 v135, vcc_lo, v206
	v_mbcnt_hi_u32_b32 v135, vcc_hi, v135
	v_lshl_add_u32 v136, v135, 2, s58
	ds_write_b32 v136, v118
	v_add_u16_e32 v136, 0x1c40, v134
	v_lshl_add_u32 v135, v135, 1, s92
	ds_write_b16 v135, v136
.LBB0_4061:
	s_or_b64 exec, exec, s[6:7]
	v_bcnt_u32_b32 v206, vcc_lo, v206
	v_bcnt_u32_b32 v206, vcc_hi, v206
	v_cmp_ge_u32_e32 vcc, v123, v3
	s_and_saveexec_b64 s[6:7], vcc
	s_cbranch_execz .LBB0_4063
	v_mbcnt_lo_u32_b32 v135, vcc_lo, v206
	v_mbcnt_hi_u32_b32 v135, vcc_hi, v135
	v_lshl_add_u32 v136, v135, 2, s58
	ds_write_b32 v136, v123
	v_add_u16_e32 v136, 0x1c80, v134
	v_lshl_add_u32 v135, v135, 1, s92
	ds_write_b16 v135, v136
.LBB0_4063:
	s_or_b64 exec, exec, s[6:7]
	v_bcnt_u32_b32 v206, vcc_lo, v206
	v_bcnt_u32_b32 v206, vcc_hi, v206
	v_cmp_ge_u32_e32 vcc, v120, v3
	s_and_saveexec_b64 s[6:7], vcc
	s_cbranch_execz .LBB0_4065
	v_mbcnt_lo_u32_b32 v135, vcc_lo, v206
	v_mbcnt_hi_u32_b32 v135, vcc_hi, v135
	v_lshl_add_u32 v136, v135, 2, s58
	ds_write_b32 v136, v120
	v_add_u16_e32 v136, 0x1cc0, v134
	v_lshl_add_u32 v135, v135, 1, s92
	ds_write_b16 v135, v136
.LBB0_4065:
	s_or_b64 exec, exec, s[6:7]
	v_bcnt_u32_b32 v206, vcc_lo, v206
	v_bcnt_u32_b32 v206, vcc_hi, v206
	v_cmp_ge_u32_e32 vcc, v125, v3
	s_and_saveexec_b64 s[6:7], vcc
	s_cbranch_execz .LBB0_4067
	v_mbcnt_lo_u32_b32 v135, vcc_lo, v206
	v_mbcnt_hi_u32_b32 v135, vcc_hi, v135
	v_lshl_add_u32 v136, v135, 2, s58
	ds_write_b32 v136, v125
	v_add_u16_e32 v136, 0x1d00, v134
	v_lshl_add_u32 v135, v135, 1, s92
	ds_write_b16 v135, v136
.LBB0_4067:
	s_or_b64 exec, exec, s[6:7]
	v_bcnt_u32_b32 v206, vcc_lo, v206
	v_bcnt_u32_b32 v206, vcc_hi, v206
	v_cmp_ge_u32_e32 vcc, v121, v3
	s_and_saveexec_b64 s[6:7], vcc
	s_cbranch_execz .LBB0_4069
	v_mbcnt_lo_u32_b32 v135, vcc_lo, v206
	v_mbcnt_hi_u32_b32 v135, vcc_hi, v135
	v_lshl_add_u32 v136, v135, 2, s58
	ds_write_b32 v136, v121
	v_add_u16_e32 v136, 0x1d40, v134
	v_lshl_add_u32 v135, v135, 1, s92
	ds_write_b16 v135, v136
.LBB0_4069:
	s_or_b64 exec, exec, s[6:7]
	v_bcnt_u32_b32 v206, vcc_lo, v206
	v_bcnt_u32_b32 v206, vcc_hi, v206
	v_cmp_ge_u32_e32 vcc, v127, v3
	s_and_saveexec_b64 s[6:7], vcc
	s_cbranch_execz .LBB0_4071
	v_mbcnt_lo_u32_b32 v135, vcc_lo, v206
	v_mbcnt_hi_u32_b32 v135, vcc_hi, v135
	v_lshl_add_u32 v136, v135, 2, s58
	ds_write_b32 v136, v127
	v_add_u16_e32 v136, 0x1d80, v134
	v_lshl_add_u32 v135, v135, 1, s92
	ds_write_b16 v135, v136
.LBB0_4071:
	s_or_b64 exec, exec, s[6:7]
	v_bcnt_u32_b32 v206, vcc_lo, v206
	v_bcnt_u32_b32 v206, vcc_hi, v206
	v_cmp_ge_u32_e32 vcc, v122, v3
	s_and_saveexec_b64 s[6:7], vcc
	s_cbranch_execz .LBB0_4073
	v_mbcnt_lo_u32_b32 v135, vcc_lo, v206
	v_mbcnt_hi_u32_b32 v135, vcc_hi, v135
	v_lshl_add_u32 v136, v135, 2, s58
	ds_write_b32 v136, v122
	v_add_u16_e32 v136, 0x1dc0, v134
	v_lshl_add_u32 v135, v135, 1, s92
	ds_write_b16 v135, v136
.LBB0_4073:
	s_or_b64 exec, exec, s[6:7]
	v_bcnt_u32_b32 v206, vcc_lo, v206
	v_bcnt_u32_b32 v206, vcc_hi, v206
	v_cmp_ge_u32_e32 vcc, v129, v3
	s_and_saveexec_b64 s[6:7], vcc
	s_cbranch_execz .LBB0_4075
	v_mbcnt_lo_u32_b32 v135, vcc_lo, v206
	v_mbcnt_hi_u32_b32 v135, vcc_hi, v135
	v_lshl_add_u32 v136, v135, 2, s58
	ds_write_b32 v136, v129
	v_add_u16_e32 v136, 0x1e00, v134
	v_lshl_add_u32 v135, v135, 1, s92
	ds_write_b16 v135, v136
.LBB0_4075:
	s_or_b64 exec, exec, s[6:7]
	v_bcnt_u32_b32 v206, vcc_lo, v206
	v_bcnt_u32_b32 v206, vcc_hi, v206
	v_cmp_ge_u32_e32 vcc, v124, v3
	s_and_saveexec_b64 s[6:7], vcc
	s_cbranch_execz .LBB0_4077
	v_mbcnt_lo_u32_b32 v135, vcc_lo, v206
	v_mbcnt_hi_u32_b32 v135, vcc_hi, v135
	v_lshl_add_u32 v136, v135, 2, s58
	ds_write_b32 v136, v124
	v_add_u16_e32 v136, 0x1e40, v134
	v_lshl_add_u32 v135, v135, 1, s92
	ds_write_b16 v135, v136
.LBB0_4077:
	s_or_b64 exec, exec, s[6:7]
	v_bcnt_u32_b32 v206, vcc_lo, v206
	v_bcnt_u32_b32 v206, vcc_hi, v206
	v_cmp_ge_u32_e32 vcc, v131, v3
	s_and_saveexec_b64 s[6:7], vcc
	s_cbranch_execz .LBB0_4079
	v_mbcnt_lo_u32_b32 v135, vcc_lo, v206
	v_mbcnt_hi_u32_b32 v135, vcc_hi, v135
	v_lshl_add_u32 v136, v135, 2, s58
	ds_write_b32 v136, v131
	v_add_u16_e32 v136, 0x1e80, v134
	v_lshl_add_u32 v135, v135, 1, s92
	ds_write_b16 v135, v136
.LBB0_4079:
	s_or_b64 exec, exec, s[6:7]
	v_bcnt_u32_b32 v206, vcc_lo, v206
	v_bcnt_u32_b32 v206, vcc_hi, v206
	v_cmp_ge_u32_e32 vcc, v126, v3
	s_and_saveexec_b64 s[6:7], vcc
	s_cbranch_execz .LBB0_4081
	v_mbcnt_lo_u32_b32 v135, vcc_lo, v206
	v_mbcnt_hi_u32_b32 v135, vcc_hi, v135
	v_lshl_add_u32 v136, v135, 2, s58
	ds_write_b32 v136, v126
	v_add_u16_e32 v136, 0x1ec0, v134
	v_lshl_add_u32 v135, v135, 1, s92
	ds_write_b16 v135, v136
.LBB0_4081:
	s_or_b64 exec, exec, s[6:7]
	v_bcnt_u32_b32 v206, vcc_lo, v206
	v_bcnt_u32_b32 v206, vcc_hi, v206
	v_cmp_ge_u32_e32 vcc, v132, v3
	s_and_saveexec_b64 s[6:7], vcc
	s_cbranch_execz .LBB0_4083
	v_mbcnt_lo_u32_b32 v135, vcc_lo, v206
	v_mbcnt_hi_u32_b32 v135, vcc_hi, v135
	v_lshl_add_u32 v136, v135, 2, s58
	ds_write_b32 v136, v132
	v_add_u16_e32 v136, 0x1f00, v134
	v_lshl_add_u32 v135, v135, 1, s92
	ds_write_b16 v135, v136
.LBB0_4083:
	s_or_b64 exec, exec, s[6:7]
	v_bcnt_u32_b32 v206, vcc_lo, v206
	v_bcnt_u32_b32 v206, vcc_hi, v206
	v_cmp_ge_u32_e32 vcc, v128, v3
	s_and_saveexec_b64 s[6:7], vcc
	s_cbranch_execz .LBB0_4085
	v_mbcnt_lo_u32_b32 v135, vcc_lo, v206
	v_mbcnt_hi_u32_b32 v135, vcc_hi, v135
	v_lshl_add_u32 v136, v135, 2, s58
	ds_write_b32 v136, v128
	v_add_u16_e32 v136, 0x1f40, v134
	v_lshl_add_u32 v135, v135, 1, s92
	ds_write_b16 v135, v136
.LBB0_4085:
	s_or_b64 exec, exec, s[6:7]
	v_bcnt_u32_b32 v206, vcc_lo, v206
	v_bcnt_u32_b32 v206, vcc_hi, v206
	v_cmp_ge_u32_e32 vcc, v133, v3
	s_and_saveexec_b64 s[6:7], vcc
	s_cbranch_execz .LBB0_4087
	v_mbcnt_lo_u32_b32 v135, vcc_lo, v206
	v_mbcnt_hi_u32_b32 v135, vcc_hi, v135
	v_lshl_add_u32 v136, v135, 2, s58
	ds_write_b32 v136, v133
	v_add_u16_e32 v136, 0x1f80, v134
	v_lshl_add_u32 v135, v135, 1, s92
	ds_write_b16 v135, v136
.LBB0_4087:
	s_or_b64 exec, exec, s[6:7]
	v_cmp_ge_u32_e64 s[6:7], v130, v3
	s_and_saveexec_b64 s[8:9], s[6:7]
	s_cbranch_execz .LBB0_4089
	v_bcnt_u32_b32 v206, vcc_lo, v206
	v_bcnt_u32_b32 v206, vcc_hi, v206
	v_mbcnt_lo_u32_b32 v3, s6, v206
	v_mbcnt_hi_u32_b32 v3, s7, v3
	v_lshl_add_u32 v135, v3, 2, s58
	v_add_u16_e32 v134, 0x1fc0, v134
	v_lshl_add_u32 v3, v3, 1, s92
	ds_write_b32 v135, v130
	ds_write_b16 v3, v134
